# EpiKV: V^T quads transposed in-register -> one 8-byte store per quad (32 instead of 128 store instr per wave); the eight rstd loads issued together at the epilogue start
# speedup vs baseline: 1.0129x; 1.0031x over previous
; #define PG8_STAGE(bufoff, gbase, soff, voff) do { _Pragma("unroll") for (int _i = 0; _i < 2; ++_i) \
;         __builtin_amdgcn_global_load_lds((const unsigned*)(((gbase) + (size_t)(unsigned)(soff)) + (voff)[_i]), (LAS unsigned*)(lds + (bufoff) + ldsw + _i * 8192), 16, 0, 0); } while (0)
; #define PG8_LDA(dst, b, h) do { _Pragma("unroll") for (int m = 0; m < 4; ++m) _Pragma("unroll") for (int k = 0; k < 2; ++k) dst[m][k] = *(const LAS bf16x8*)(lds + PG8_SA(b, h) + aoff + m * 2048 + k * 1024); } while (0)
; #define PG8_LDB(dst, b, h) do { _Pragma("unroll") for (int n = 0; n < 2; ++n) _Pragma("unroll") for (int k = 0; k < 2; ++k) dst[n][k] = *(const LAS bf16x8*)(lds + PG8_SB(b, h) + boff + n * 2048 + k * 1024); } while (0)
; #define PG8_MMA(ai, bj, At, Bt) do { __builtin_amdgcn_s_setprio(1); _Pragma("unroll") for (int m = 0; m < 4; ++m) _Pragma("unroll") for (int n = 0; n < 2; ++n) _Pragma("unroll") for (int k = 0; k < 2; ++k) \
;         acc[ai][bj][m][n] = __builtin_amdgcn_mfma_f32_16x16x32_bf16(Bt[n][k], At[m][k], acc[ai][bj][m][n], 0, 0, 0); __builtin_amdgcn_s_setprio(0); } while (0)
; #define PG8_WAIT_V(n) asm volatile("s_waitcnt vmcnt(" #n ")" ::: "memory")
; #define PG8_WAIT_L(n) asm volatile("s_waitcnt lgkmcnt(" #n ")" ::: "memory")
; #define PG8_BAR __builtin_amdgcn_s_barrier()
; #define PG8_SCHED __builtin_amdgcn_sched_barrier(0)
; template <class Epi>
; __device__ __forceinline__ void gemm_phase(LAS unsigned char* lds, const Gemm g, const StaticOrder& S, const Epi& E, const int tid) {
;     ...
;             PG8_LDB(B0, 0, 0); PG8_SCHED; PG8_LDA(At, 0, 0); PG8_STAGE(PG8_SA(1, 1), gA, a1 + hstepA, voffA);
;             PG8_WAIT_L(8); PG8_BAR; PG8_WAIT_L(0); PG8_MMA(0, 0, At, B0); PG8_BAR; PG8_SCHED;
;             PG8_LDB(B1, 0, 1); PG8_STAGE(PG8_SB(0, 0), gB, b2, voffB);
;             PG8_BAR; PG8_WAIT_L(0); PG8_MMA(0, 1, At, B1); PG8_BAR;
;             PG8_LDA(At, 0, 1); PG8_STAGE(PG8_SA(0, 0), gA, a2, voffA);
;             PG8_BAR; PG8_WAIT_L(0); PG8_MMA(1, 0, At, B0); PG8_BAR; PG8_SCHED;
;             PG8_STAGE(PG8_SB(0, 1), gB, b2 + hstepB, voffB);
;             PG8_WAIT_V(6); PG8_BAR; PG8_MMA(1, 1, At, B1); PG8_BAR;
.LBB0_549:
	s_add_i32 s8, s4, s6
	s_addk_i32 s8, 0x100
	s_add_i32 s9, s5, s6
	s_cmpk_eq_i32 s6, 0x700
	s_cselect_b32 s62, s26, s8
	s_cselect_b32 s73, s27, s9
	s_add_i32 s9, 0, 0x10000
	v_add_u32_e32 v0, s9, v175
	ds_read_b128 v[150:153], v0
	ds_read_b128 v[154:157], v0 offset:1024
	ds_read_b128 v[158:161], v0 offset:2048
	ds_read_b128 v[162:165], v0 offset:3072
	s_or_b32 s8, s62, 0x80
	v_lshl_add_u64 v[186:187], v[146:147], 0, s[6:7]
	s_add_i32 m0, s31, 0xc000
	ds_read_b128 v[166:169], v177
	ds_read_b128 v[170:173], v177 offset:1024
	ds_read_b128 v[178:181], v177 offset:2048
	ds_read_b128 v[182:185], v177 offset:3072
	ds_read_b128 v[194:197], v177 offset:4096
	ds_read_b128 v[198:201], v177 offset:5120
	ds_read_b128 v[202:205], v177 offset:6144
	ds_read_b128 v[206:209], v177 offset:7168
	global_load_lds_dwordx4 v[186:187], off
	v_lshl_add_u64 v[186:187], v[148:149], 0, s[6:7]
	s_add_i32 m0, s31, 0xe000
	s_nop 0
	global_load_lds_dwordx4 v[186:187], off
	s_waitcnt lgkmcnt(8)
	s_barrier
	s_waitcnt lgkmcnt(0)
	s_setprio 1
	s_waitcnt lgkmcnt(0)
	v_mfma_f32_16x16x32_bf16 v[126:129], v[150:153], v[166:169], v[126:129]
	v_mfma_f32_16x16x32_bf16 v[122:125], v[158:161], v[166:169], v[122:125]
	v_mfma_f32_16x16x32_bf16 v[110:113], v[150:153], v[178:181], v[110:113]
	v_mfma_f32_16x16x32_bf16 v[106:109], v[158:161], v[178:181], v[106:109]
	v_mfma_f32_16x16x32_bf16 v[94:97], v[150:153], v[194:197], v[94:97]
	v_mfma_f32_16x16x32_bf16 v[90:93], v[158:161], v[194:197], v[90:93]
	v_mfma_f32_16x16x32_bf16 v[78:81], v[150:153], v[202:205], v[78:81]
	v_mfma_f32_16x16x32_bf16 v[74:77], v[158:161], v[202:205], v[74:77]
	v_mfma_f32_16x16x32_bf16 v[126:129], v[154:157], v[170:173], v[126:129]
	v_mfma_f32_16x16x32_bf16 v[122:125], v[162:165], v[170:173], v[122:125]
	v_mfma_f32_16x16x32_bf16 v[110:113], v[154:157], v[182:185], v[110:113]
	v_mfma_f32_16x16x32_bf16 v[106:109], v[162:165], v[182:185], v[106:109]
	v_mfma_f32_16x16x32_bf16 v[94:97], v[154:157], v[198:201], v[94:97]
	v_mfma_f32_16x16x32_bf16 v[90:93], v[162:165], v[198:201], v[90:93]
	v_mfma_f32_16x16x32_bf16 v[78:81], v[154:157], v[206:209], v[78:81]
	v_mfma_f32_16x16x32_bf16 v[74:77], v[162:165], v[206:209], v[74:77]
	s_setprio 0
	s_barrier
	s_add_i32 s88, 0, 0x14000
	s_add_u32 s74, s14, s73
	s_addc_u32 s75, s15, 0
	s_add_i32 s9, s9, s30
	v_add_u32_e32 v0, s88, v175
	v_lshl_add_u64 v[186:187], s[74:75], 0, v[130:131]
	s_mov_b32 m0, s9
	ds_read_b128 v[210:213], v0
	ds_read_b128 v[214:217], v0 offset:1024
	ds_read_b128 v[218:221], v0 offset:2048
	ds_read_b128 v[222:225], v0 offset:3072
	global_load_lds_dwordx4 v[186:187], off
	v_lshl_add_u64 v[186:187], s[74:75], 0, v[132:133]
	s_add_i32 m0, s9, 0x2000
	s_nop 0
	global_load_lds_dwordx4 v[186:187], off
	s_barrier
	s_waitcnt lgkmcnt(0)
	s_setprio 1
	s_waitcnt lgkmcnt(0)
	v_mfma_f32_16x16x32_bf16 v[118:121], v[210:213], v[166:169], v[118:121]
	v_mfma_f32_16x16x32_bf16 v[114:117], v[218:221], v[166:169], v[114:117]
	v_mfma_f32_16x16x32_bf16 v[102:105], v[210:213], v[178:181], v[102:105]
	v_mfma_f32_16x16x32_bf16 v[98:101], v[218:221], v[178:181], v[98:101]
	v_mfma_f32_16x16x32_bf16 v[86:89], v[210:213], v[194:197], v[86:89]
	v_mfma_f32_16x16x32_bf16 v[82:85], v[218:221], v[194:197], v[82:85]
	v_mfma_f32_16x16x32_bf16 v[70:73], v[210:213], v[202:205], v[70:73]
	v_mfma_f32_16x16x32_bf16 v[66:69], v[218:221], v[202:205], v[66:69]
	v_mfma_f32_16x16x32_bf16 v[118:121], v[214:217], v[170:173], v[118:121]
	v_mfma_f32_16x16x32_bf16 v[114:117], v[222:225], v[170:173], v[114:117]
	v_mfma_f32_16x16x32_bf16 v[102:105], v[214:217], v[182:185], v[102:105]
	v_mfma_f32_16x16x32_bf16 v[98:101], v[222:225], v[182:185], v[98:101]
	v_mfma_f32_16x16x32_bf16 v[86:89], v[214:217], v[198:201], v[86:89]
	v_mfma_f32_16x16x32_bf16 v[82:85], v[222:225], v[198:201], v[82:85]
	v_mfma_f32_16x16x32_bf16 v[70:73], v[214:217], v[206:209], v[70:73]
	v_mfma_f32_16x16x32_bf16 v[66:69], v[222:225], v[206:209], v[66:69]
	s_setprio 0
	s_add_u32 s74, s12, s62
	s_addc_u32 s75, s13, 0
	s_mov_b32 m0, s31
	v_lshl_add_u64 v[186:187], s[74:75], 0, v[130:131]
	s_barrier
	ds_read_b128 v[166:169], v177 offset:16384
	ds_read_b128 v[170:173], v177 offset:17408
	ds_read_b128 v[178:181], v177 offset:18432
	ds_read_b128 v[182:185], v177 offset:19456
	ds_read_b128 v[194:197], v177 offset:20480
	ds_read_b128 v[198:201], v177 offset:21504
	ds_read_b128 v[202:205], v177 offset:22528
	ds_read_b128 v[206:209], v177 offset:23552
	global_load_lds_dwordx4 v[186:187], off
	v_lshl_add_u64 v[186:187], s[74:75], 0, v[132:133]
	s_mov_b32 m0, s34
	s_nop 0
	global_load_lds_dwordx4 v[186:187], off
	s_barrier
	s_waitcnt lgkmcnt(0)
	s_setprio 1
	s_waitcnt lgkmcnt(0)
	v_mfma_f32_16x16x32_bf16 v[62:65], v[150:153], v[166:169], v[62:65]
	v_mfma_f32_16x16x32_bf16 v[58:61], v[158:161], v[166:169], v[58:61]
	v_mfma_f32_16x16x32_bf16 v[46:49], v[150:153], v[178:181], v[46:49]
	v_mfma_f32_16x16x32_bf16 v[42:45], v[158:161], v[178:181], v[42:45]
	v_mfma_f32_16x16x32_bf16 v[30:33], v[150:153], v[194:197], v[30:33]
	v_mfma_f32_16x16x32_bf16 v[26:29], v[158:161], v[194:197], v[26:29]
	v_mfma_f32_16x16x32_bf16 v[14:17], v[150:153], v[202:205], v[14:17]
	v_mfma_f32_16x16x32_bf16 v[10:13], v[158:161], v[202:205], v[10:13]
	v_mfma_f32_16x16x32_bf16 v[62:65], v[154:157], v[170:173], v[62:65]
	v_mfma_f32_16x16x32_bf16 v[58:61], v[162:165], v[170:173], v[58:61]
	v_mfma_f32_16x16x32_bf16 v[46:49], v[154:157], v[182:185], v[46:49]
	v_mfma_f32_16x16x32_bf16 v[42:45], v[162:165], v[182:185], v[42:45]
	v_mfma_f32_16x16x32_bf16 v[30:33], v[154:157], v[198:201], v[30:33]
	v_mfma_f32_16x16x32_bf16 v[26:29], v[162:165], v[198:201], v[26:29]
	v_mfma_f32_16x16x32_bf16 v[14:17], v[154:157], v[206:209], v[14:17]
	v_mfma_f32_16x16x32_bf16 v[10:13], v[162:165], v[206:209], v[10:13]
	s_setprio 0
	s_barrier
; #define PG8_STAGE(bufoff, gbase, soff, voff) do { _Pragma("unroll") for (int _i = 0; _i < 2; ++_i) \
;         __builtin_amdgcn_global_load_lds((const unsigned*)(((gbase) + (size_t)(unsigned)(soff)) + (voff)[_i]), (LAS unsigned*)(lds + (bufoff) + ldsw + _i * 8192), 16, 0, 0); } while (0)
; #define PG8_LDA(dst, b, h) do { _Pragma("unroll") for (int m = 0; m < 4; ++m) _Pragma("unroll") for (int k = 0; k < 2; ++k) dst[m][k] = *(const LAS bf16x8*)(lds + PG8_SA(b, h) + aoff + m * 2048 + k * 1024); } while (0)
; #define PG8_LDB(dst, b, h) do { _Pragma("unroll") for (int n = 0; n < 2; ++n) _Pragma("unroll") for (int k = 0; k < 2; ++k) dst[n][k] = *(const LAS bf16x8*)(lds + PG8_SB(b, h) + boff + n * 2048 + k * 1024); } while (0)
; #define PG8_MMA(ai, bj, At, Bt) do { __builtin_amdgcn_s_setprio(1); _Pragma("unroll") for (int m = 0; m < 4; ++m) _Pragma("unroll") for (int n = 0; n < 2; ++n) _Pragma("unroll") for (int k = 0; k < 2; ++k) \
;         acc[ai][bj][m][n] = __builtin_amdgcn_mfma_f32_16x16x32_bf16(Bt[n][k], At[m][k], acc[ai][bj][m][n], 0, 0, 0); __builtin_amdgcn_s_setprio(0); } while (0)
; #define PG8_WAIT_V(n) asm volatile("s_waitcnt vmcnt(" #n ")" ::: "memory")
; #define PG8_WAIT_L(n) asm volatile("s_waitcnt lgkmcnt(" #n ")" ::: "memory")
; #define PG8_BAR __builtin_amdgcn_s_barrier()
; #define PG8_SCHED __builtin_amdgcn_sched_barrier(0)
; template <class Epi>
; __device__ __forceinline__ void gemm_phase(LAS unsigned char* lds, const Gemm g, const StaticOrder& S, const Epi& E, const int tid) {
;     ...
;             PG8_WAIT_V(6); PG8_BAR; PG8_MMA(1, 1, At, B1); PG8_BAR;
;             PG8_LDB(B0, 1, 0); PG8_SCHED; PG8_LDA(At, 1, 0); PG8_STAGE(PG8_SA(0, 1), gA, a2 + hstepA, voffA);
;             PG8_WAIT_L(8); PG8_BAR; PG8_WAIT_L(0); PG8_MMA(0, 0, At, B0); PG8_BAR; PG8_SCHED;
;             PG8_LDB(B1, 1, 1); PG8_STAGE(PG8_SB(1, 0), gB, b3, voffB);
;             PG8_BAR; PG8_WAIT_L(0); PG8_MMA(0, 1, At, B1); PG8_BAR;
;             PG8_LDA(At, 1, 1); PG8_STAGE(PG8_SA(1, 0), gA, a3, voffA);
;             PG8_BAR; PG8_WAIT_L(0); PG8_MMA(1, 0, At, B0); PG8_BAR; PG8_SCHED;
	s_add_i32 s9, s73, 0x40000
	s_add_u32 s74, s14, s9
	s_addc_u32 s75, s15, 0
	s_add_i32 s9, s88, s30
	v_lshl_add_u64 v[150:151], s[74:75], 0, v[130:131]
	s_mov_b32 m0, s9
	s_nop 0
	global_load_lds_dwordx4 v[150:151], off
	v_lshl_add_u64 v[150:151], s[74:75], 0, v[132:133]
	s_add_i32 m0, s9, 0x2000
	s_nop 0
	global_load_lds_dwordx4 v[150:151], off
	s_waitcnt vmcnt(6)
	s_barrier
	s_setprio 1
	v_mfma_f32_16x16x32_bf16 v[54:57], v[210:213], v[166:169], v[54:57]
	v_mfma_f32_16x16x32_bf16 v[50:53], v[218:221], v[166:169], v[50:53]
	v_mfma_f32_16x16x32_bf16 v[38:41], v[210:213], v[178:181], v[38:41]
	v_mfma_f32_16x16x32_bf16 v[34:37], v[218:221], v[178:181], v[34:37]
	v_mfma_f32_16x16x32_bf16 v[22:25], v[210:213], v[194:197], v[22:25]
	v_mfma_f32_16x16x32_bf16 v[18:21], v[218:221], v[194:197], v[18:21]
	v_mfma_f32_16x16x32_bf16 v[6:9], v[210:213], v[202:205], v[6:9]
	v_mfma_f32_16x16x32_bf16 v[2:5], v[218:221], v[202:205], v[2:5]
	v_mfma_f32_16x16x32_bf16 v[54:57], v[214:217], v[170:173], v[54:57]
	v_mfma_f32_16x16x32_bf16 v[50:53], v[222:225], v[170:173], v[50:53]
	v_mfma_f32_16x16x32_bf16 v[38:41], v[214:217], v[182:185], v[38:41]
	v_mfma_f32_16x16x32_bf16 v[34:37], v[222:225], v[182:185], v[34:37]
	v_mfma_f32_16x16x32_bf16 v[22:25], v[214:217], v[198:201], v[22:25]
	v_mfma_f32_16x16x32_bf16 v[18:21], v[222:225], v[198:201], v[18:21]
	v_mfma_f32_16x16x32_bf16 v[6:9], v[214:217], v[206:209], v[6:9]
	v_mfma_f32_16x16x32_bf16 v[2:5], v[222:225], v[206:209], v[2:5]
	s_setprio 0
	s_add_i32 s9, 0, 0x18000
	v_add_u32_e32 v0, s9, v175
	s_barrier
	ds_read_b128 v[150:153], v0
	ds_read_b128 v[154:157], v0 offset:1024
	ds_read_b128 v[158:161], v0 offset:2048
	ds_read_b128 v[162:165], v0 offset:3072
	s_add_i32 s62, s62, 0x40000
	s_add_u32 s74, s12, s62
	s_addc_u32 s75, s13, 0
	s_mov_b32 m0, s35
	v_lshl_add_u64 v[186:187], s[74:75], 0, v[130:131]
	ds_read_b128 v[166:169], v177 offset:32768
	ds_read_b128 v[170:173], v177 offset:33792
	ds_read_b128 v[178:181], v177 offset:34816
	ds_read_b128 v[182:185], v177 offset:35840
	ds_read_b128 v[194:197], v177 offset:36864
	ds_read_b128 v[198:201], v177 offset:37888
	ds_read_b128 v[202:205], v177 offset:38912
	ds_read_b128 v[206:209], v177 offset:39936
	global_load_lds_dwordx4 v[186:187], off
	v_lshl_add_u64 v[186:187], s[74:75], 0, v[132:133]
	s_mov_b32 m0, s38
	s_nop 0
	global_load_lds_dwordx4 v[186:187], off
	s_waitcnt lgkmcnt(8)
	s_barrier
	s_waitcnt lgkmcnt(0)
	s_setprio 1
	s_waitcnt lgkmcnt(0)
	v_mfma_f32_16x16x32_bf16 v[126:129], v[150:153], v[166:169], v[126:129]
	v_mfma_f32_16x16x32_bf16 v[122:125], v[158:161], v[166:169], v[122:125]
	v_mfma_f32_16x16x32_bf16 v[110:113], v[150:153], v[178:181], v[110:113]
	v_mfma_f32_16x16x32_bf16 v[106:109], v[158:161], v[178:181], v[106:109]
	v_mfma_f32_16x16x32_bf16 v[94:97], v[150:153], v[194:197], v[94:97]
	v_mfma_f32_16x16x32_bf16 v[90:93], v[158:161], v[194:197], v[90:93]
	v_mfma_f32_16x16x32_bf16 v[78:81], v[150:153], v[202:205], v[78:81]
	v_mfma_f32_16x16x32_bf16 v[74:77], v[158:161], v[202:205], v[74:77]
	v_mfma_f32_16x16x32_bf16 v[126:129], v[154:157], v[170:173], v[126:129]
	v_mfma_f32_16x16x32_bf16 v[122:125], v[162:165], v[170:173], v[122:125]
	v_mfma_f32_16x16x32_bf16 v[110:113], v[154:157], v[182:185], v[110:113]
	v_mfma_f32_16x16x32_bf16 v[106:109], v[162:165], v[182:185], v[106:109]
	v_mfma_f32_16x16x32_bf16 v[94:97], v[154:157], v[198:201], v[94:97]
	v_mfma_f32_16x16x32_bf16 v[90:93], v[162:165], v[198:201], v[90:93]
	v_mfma_f32_16x16x32_bf16 v[78:81], v[154:157], v[206:209], v[78:81]
	v_mfma_f32_16x16x32_bf16 v[74:77], v[162:165], v[206:209], v[74:77]
	s_setprio 0
	s_barrier
	s_add_i32 s74, 0, 0x1c000
	s_or_b32 s62, s73, 0x80
	s_add_i32 s9, s9, s30
	v_add_u32_e32 v0, s74, v175
	v_lshl_add_u64 v[186:187], v[134:135], 0, s[62:63]
	s_mov_b32 m0, s9
	ds_read_b128 v[210:213], v0
	ds_read_b128 v[214:217], v0 offset:1024
	ds_read_b128 v[218:221], v0 offset:2048
	ds_read_b128 v[222:225], v0 offset:3072
	global_load_lds_dwordx4 v[186:187], off
	v_lshl_add_u64 v[186:187], v[136:137], 0, s[62:63]
	s_add_i32 m0, s9, 0x2000
	s_nop 0
	global_load_lds_dwordx4 v[186:187], off
	s_barrier
	s_waitcnt lgkmcnt(0)
	s_setprio 1
	s_waitcnt lgkmcnt(0)
	v_mfma_f32_16x16x32_bf16 v[118:121], v[210:213], v[166:169], v[118:121]
	v_mfma_f32_16x16x32_bf16 v[114:117], v[218:221], v[166:169], v[114:117]
	v_mfma_f32_16x16x32_bf16 v[102:105], v[210:213], v[178:181], v[102:105]
	v_mfma_f32_16x16x32_bf16 v[98:101], v[218:221], v[178:181], v[98:101]
	v_mfma_f32_16x16x32_bf16 v[86:89], v[210:213], v[194:197], v[86:89]
	v_mfma_f32_16x16x32_bf16 v[82:85], v[218:221], v[194:197], v[82:85]
	v_mfma_f32_16x16x32_bf16 v[70:73], v[210:213], v[202:205], v[70:73]
	v_mfma_f32_16x16x32_bf16 v[66:69], v[218:221], v[202:205], v[66:69]
	v_mfma_f32_16x16x32_bf16 v[118:121], v[214:217], v[170:173], v[118:121]
	v_mfma_f32_16x16x32_bf16 v[114:117], v[222:225], v[170:173], v[114:117]
	v_mfma_f32_16x16x32_bf16 v[102:105], v[214:217], v[182:185], v[102:105]
	v_mfma_f32_16x16x32_bf16 v[98:101], v[222:225], v[182:185], v[98:101]
	v_mfma_f32_16x16x32_bf16 v[86:89], v[214:217], v[198:201], v[86:89]
	v_mfma_f32_16x16x32_bf16 v[82:85], v[222:225], v[198:201], v[82:85]
	v_mfma_f32_16x16x32_bf16 v[70:73], v[214:217], v[206:209], v[70:73]
	v_mfma_f32_16x16x32_bf16 v[66:69], v[222:225], v[206:209], v[66:69]
	s_setprio 0
	s_mov_b32 s9, s63
	s_mov_b32 m0, s44
	v_lshl_add_u64 v[186:187], v[138:139], 0, s[8:9]
	s_barrier
; __device__ __forceinline__ bf16_t f2bf(float x) { return (bf16_t)(cvt_pk_bf16(x, 0.f) & 0xffffu); }
; __device__ __forceinline__ void st_bf4(bf16_t* p, f32x4 v) { u32x2 w; w.x = cvt_pk_bf16(v[0], v[1]); w.y = cvt_pk_bf16(v[2], v[3]); *(u32x2*)p = w; }
; #define PG8_STAGE(bufoff, gbase, soff, voff) do { _Pragma("unroll") for (int _i = 0; _i < 2; ++_i) \
;         __builtin_amdgcn_global_load_lds((const unsigned*)(((gbase) + (size_t)(unsigned)(soff)) + (voff)[_i]), (LAS unsigned*)(lds + (bufoff) + ldsw + _i * 8192), 16, 0, 0); } while (0)
; #define PG8_MMA(ai, bj, At, Bt) do { __builtin_amdgcn_s_setprio(1); _Pragma("unroll") for (int m = 0; m < 4; ++m) _Pragma("unroll") for (int n = 0; n < 2; ++n) _Pragma("unroll") for (int k = 0; k < 2; ++k) \
;         acc[ai][bj][m][n] = __builtin_amdgcn_mfma_f32_16x16x32_bf16(Bt[n][k], At[m][k], acc[ai][bj][m][n], 0, 0, 0); __builtin_amdgcn_s_setprio(0); } while (0)
; #define PG8_WAIT_V(n) asm volatile("s_waitcnt vmcnt(" #n ")" ::: "memory")
; #define PG8_WAIT_L(n) asm volatile("s_waitcnt lgkmcnt(" #n ")" ::: "memory")
; template <class Epi>
; __device__ __forceinline__ void gemm_phase(LAS unsigned char* lds, const Gemm g, const StaticOrder& S, const Epi& E, const int tid) {
;     ...
;             PG8_BAR; PG8_WAIT_L(0); PG8_MMA(1, 0, At, B0); PG8_BAR; PG8_SCHED;
;             PG8_STAGE(PG8_SB(1, 1), gB, b3 + hstepB, voffB);
;             PG8_WAIT_V(6); PG8_BAR; PG8_MMA(1, 1, At, B1); PG8_BAR;
;         }
;         E(acc, cur, wr, wc, fr, fq);
;     __device__ __forceinline__ void operator()(const Acc& acc, const Unit& u, int wr, int wc, int fr, int fq) const {
;         const int row0 = u.pm * 256 + wr * 64 + fr, col0 = u.pn * 256 + wc * 32 + 4 * fq;
; #pragma unroll
;         for (int ai = 0; ai < 2; ++ai)
; #pragma unroll
;             for (int m = 0; m < 4; ++m) { const int row = row0 + ai * 128 + m * 16; const float rs = rstd[row];
; #pragma unroll
;                 for (int bj = 0; bj < 2; ++bj)
; #pragma unroll
;                     for (int n = 0; n < 2; ++n) { const int col = col0 + bj * 128 + n * 16; const f32x4 v = acc[ai][bj][m][n] * rs;
;                         if (col < 512) st_bf4(Kb + (size_t)row * 512 + col, v);
;                         else {
; #pragma unroll
;                             for (int j = 0; j < 4; ++j) Vt[((size_t)(row >> 8) * 512 + (col - 512 + j)) * 256 + (row & 255)] = f2bf(v[j]); } } }
	ds_read_b128 v[166:169], v177 offset:49152
	ds_read_b128 v[170:173], v177 offset:50176
	ds_read_b128 v[178:181], v177 offset:51200
	ds_read_b128 v[182:185], v177 offset:52224
	ds_read_b128 v[194:197], v177 offset:53248
	ds_read_b128 v[198:201], v177 offset:54272
	ds_read_b128 v[202:205], v177 offset:55296
	ds_read_b128 v[206:209], v177 offset:56320
	global_load_lds_dwordx4 v[186:187], off
	v_lshl_add_u64 v[186:187], v[140:141], 0, s[8:9]
	s_mov_b32 m0, s45
	s_nop 0
	global_load_lds_dwordx4 v[186:187], off
	s_barrier
	s_waitcnt lgkmcnt(0)
	s_setprio 1
	s_waitcnt lgkmcnt(0)
	v_mfma_f32_16x16x32_bf16 v[62:65], v[150:153], v[166:169], v[62:65]
	v_mfma_f32_16x16x32_bf16 v[58:61], v[158:161], v[166:169], v[58:61]
	v_mfma_f32_16x16x32_bf16 v[46:49], v[150:153], v[178:181], v[46:49]
	v_mfma_f32_16x16x32_bf16 v[42:45], v[158:161], v[178:181], v[42:45]
	v_mfma_f32_16x16x32_bf16 v[30:33], v[150:153], v[194:197], v[30:33]
	v_mfma_f32_16x16x32_bf16 v[26:29], v[158:161], v[194:197], v[26:29]
	v_mfma_f32_16x16x32_bf16 v[14:17], v[150:153], v[202:205], v[14:17]
	v_mfma_f32_16x16x32_bf16 v[10:13], v[158:161], v[202:205], v[10:13]
	v_mfma_f32_16x16x32_bf16 v[62:65], v[154:157], v[170:173], v[62:65]
	v_mfma_f32_16x16x32_bf16 v[58:61], v[162:165], v[170:173], v[58:61]
	v_mfma_f32_16x16x32_bf16 v[46:49], v[154:157], v[182:185], v[46:49]
	v_mfma_f32_16x16x32_bf16 v[42:45], v[162:165], v[182:185], v[42:45]
	v_mfma_f32_16x16x32_bf16 v[30:33], v[154:157], v[198:201], v[30:33]
	v_mfma_f32_16x16x32_bf16 v[26:29], v[162:165], v[198:201], v[26:29]
	v_mfma_f32_16x16x32_bf16 v[14:17], v[154:157], v[206:209], v[14:17]
	v_mfma_f32_16x16x32_bf16 v[10:13], v[162:165], v[206:209], v[10:13]
	s_setprio 0
	s_barrier
	s_add_i32 s73, s73, 0x40080
	s_add_u32 s8, s14, s73
	s_addc_u32 s9, s15, 0
	s_add_i32 s62, s74, s30
	v_lshl_add_u64 v[150:151], s[8:9], 0, v[130:131]
	s_mov_b32 m0, s62
	s_nop 0
	global_load_lds_dwordx4 v[150:151], off
	v_lshl_add_u64 v[150:151], s[8:9], 0, v[132:133]
	s_add_i32 m0, s62, 0x2000
	s_nop 0
	global_load_lds_dwordx4 v[150:151], off
	s_waitcnt vmcnt(6)
	s_barrier
	s_setprio 1
	v_mfma_f32_16x16x32_bf16 v[54:57], v[210:213], v[166:169], v[54:57]
	v_mfma_f32_16x16x32_bf16 v[50:53], v[218:221], v[166:169], v[50:53]
	v_mfma_f32_16x16x32_bf16 v[38:41], v[210:213], v[178:181], v[38:41]
	v_mfma_f32_16x16x32_bf16 v[34:37], v[218:221], v[178:181], v[34:37]
	v_mfma_f32_16x16x32_bf16 v[22:25], v[210:213], v[194:197], v[22:25]
	v_mfma_f32_16x16x32_bf16 v[18:21], v[218:221], v[194:197], v[18:21]
	v_mfma_f32_16x16x32_bf16 v[6:9], v[210:213], v[202:205], v[6:9]
	v_mfma_f32_16x16x32_bf16 v[2:5], v[218:221], v[202:205], v[2:5]
	v_mfma_f32_16x16x32_bf16 v[54:57], v[214:217], v[170:173], v[54:57]
	v_mfma_f32_16x16x32_bf16 v[50:53], v[222:225], v[170:173], v[50:53]
	v_mfma_f32_16x16x32_bf16 v[38:41], v[214:217], v[182:185], v[38:41]
	v_mfma_f32_16x16x32_bf16 v[34:37], v[222:225], v[182:185], v[34:37]
	v_mfma_f32_16x16x32_bf16 v[22:25], v[214:217], v[198:201], v[22:25]
	v_mfma_f32_16x16x32_bf16 v[18:21], v[222:225], v[198:201], v[18:21]
	v_mfma_f32_16x16x32_bf16 v[6:9], v[214:217], v[206:209], v[6:9]
	v_mfma_f32_16x16x32_bf16 v[2:5], v[222:225], v[206:209], v[2:5]
	s_setprio 0
	s_add_i32 s72, s72, 2
	s_add_u32 s6, s6, 0x100
	s_addc_u32 s7, s7, 0
	s_cmp_gt_u32 s72, 13
	s_barrier
	s_cbranch_scc0 .LBB0_549
	s_mov_b32 s40, 0x55555555
	s_mov_b32 s41, 0x55555555
	s_mov_b32 s42, 0xaaaaaaaa
	s_mov_b32 s43, 0xaaaaaaaa
	s_mov_b32 s46, 0x33333333
	s_mov_b32 s47, 0x33333333
	s_mov_b32 s48, 0xcccccccc
	s_mov_b32 s49, 0xcccccccc
	v_and_b32_e32 v226, 3, v232
	v_lshlrev_b32_e32 v226, 9, v226
	s_lshl_b32 s4, s25, 8
	s_add_i32 s6, s4, s39
	v_or_b32_e32 v148, s6, v174
	v_ashrrev_i32_e32 v149, 31, v148
	v_lshl_add_u64 v[152:153], v[148:149], 2, s[10:11]
	global_load_dword v164, v[152:153], off
	global_load_dword v194, v[152:153], off offset:64
	global_load_dword v195, v[152:153], off offset:128
	global_load_dword v196, v[152:153], off offset:192
	global_load_dword v197, v[152:153], off offset:512
	global_load_dword v198, v[152:153], off offset:576
	global_load_dword v199, v[152:153], off offset:640
	global_load_dword v200, v[152:153], off offset:704
	s_ashr_i32 s4, s6, 8
	v_mov_b32_e32 v0, 0xcf
	v_lshl_or_b32 v146, s24, 8, v176
	s_ashr_i32 s5, s4, 31
	v_bitop3_b32 v0, s6, v0, v174 bitop3:0xc8
	s_lshl_b64 s[24:25], s[4:5], 18
	v_cmp_lt_i32_e32 vcc, s59, v146
	v_add_u32_e32 v154, 0xfffffe00, v146
	v_add_u32_e32 v150, 0xfffffe01, v146
	v_lshlrev_b32_e32 v0, 1, v0
	s_waitcnt vmcnt(0)
	v_pk_mul_f32 v[156:157], v[128:129], v[164:165] op_sel_hi:[1,0]
	v_pk_mul_f32 v[158:159], v[126:127], v[164:165] op_sel_hi:[1,0]
	v_add_u32_e32 v128, 0xfffffe02, v146
	v_add_u32_e32 v126, 0xfffffe03, v146
	s_and_saveexec_b64 s[4:5], vcc
	s_xor_b64 s[4:5], exec, s[4:5]
	s_cbranch_execz .LBB0_552
	v_and_b32_e32 v192, -8, v0
	s_add_u32 s6, s18, s24
	s_addc_u32 s7, s19, s25
	s_mov_b64 s[50:51], vcc
	s_mov_b64 vcc, s[40:41]
	v_cndmask_b32_dpp v188, v159, v158, vcc quad_perm:[1,0,3,2] row_mask:0xf bank_mask:0xf
	v_cndmask_b32_dpp v190, v157, v156, vcc quad_perm:[1,0,3,2] row_mask:0xf bank_mask:0xf
	s_mov_b64 vcc, s[42:43]
	v_cndmask_b32_dpp v189, v158, v159, vcc quad_perm:[1,0,3,2] row_mask:0xf bank_mask:0xf
	v_cndmask_b32_dpp v191, v156, v157, vcc quad_perm:[1,0,3,2] row_mask:0xf bank_mask:0xf
	s_mov_b64 vcc, s[46:47]
	v_cndmask_b32_dpp v158, v190, v188, vcc quad_perm:[2,3,0,1] row_mask:0xf bank_mask:0xf
	v_cndmask_b32_dpp v159, v191, v189, vcc quad_perm:[2,3,0,1] row_mask:0xf bank_mask:0xf
	s_mov_b64 vcc, s[48:49]
	v_cndmask_b32_dpp v156, v188, v190, vcc quad_perm:[2,3,0,1] row_mask:0xf bank_mask:0xf
	v_cndmask_b32_dpp v157, v189, v191, vcc quad_perm:[2,3,0,1] row_mask:0xf bank_mask:0xf
	s_mov_b64 vcc, s[50:51]
	v_lshl_add_u32 v192, v154, 9, v192
	v_cvt_pk_bf16_f32 v157, v156, v157
	v_cvt_pk_bf16_f32 v156, v158, v159
	v_add_u32_e32 v192, v192, v226
	v_mov_b32_e32 v193, v1
	v_lshl_add_u64 v[192:193], s[6:7], 0, v[192:193]
	global_store_dwordx2 v[192:193], v[156:157], off

; __device__ __forceinline__ bf16_t f2bf(float x) { return (bf16_t)(cvt_pk_bf16(x, 0.f) & 0xffffu); }
; __device__ __forceinline__ void st_bf4(bf16_t* p, f32x4 v) { u32x2 w; w.x = cvt_pk_bf16(v[0], v[1]); w.y = cvt_pk_bf16(v[2], v[3]); *(u32x2*)p = w; }
;     __device__ __forceinline__ void operator()(const Acc& acc, const Unit& u, int wr, int wc, int fr, int fq) const {
;     ...
;                     for (int n = 0; n < 2; ++n) { const int col = col0 + bj * 128 + n * 16; const f32x4 v = acc[ai][bj][m][n] * rs;
;                         if (col < 512) st_bf4(Kb + (size_t)row * 512 + col, v);
;                         else {
; #pragma unroll
;                             for (int j = 0; j < 4; ++j) Vt[((size_t)(row >> 8) * 512 + (col - 512 + j)) * 256 + (row & 255)] = f2bf(v[j]); } } }
.LBB0_554:
	s_or_b64 exec, exec, s[4:5]
	v_mov_b32_e32 v165, v164
	v_or_b32_e32 v127, 16, v146
	v_mov_b32_e32 v156, v164
	v_mov_b32_e32 v157, v164
	v_pk_mul_f32 v[160:161], v[124:125], v[156:157]
	v_pk_mul_f32 v[162:163], v[122:123], v[164:165]
	v_cmp_lt_i32_e64 s[4:5], s59, v127
	v_add_u32_e32 v158, 0xfffffe10, v146
	v_add_u32_e32 v156, 0xfffffe11, v146
	v_add_u32_e32 v124, 0xfffffe12, v146
	v_add_u32_e32 v122, 0xfffffe13, v146
	s_and_saveexec_b64 s[6:7], s[4:5]
	s_xor_b64 s[6:7], exec, s[6:7]
	s_cbranch_execz .LBB0_556
	v_and_b32_e32 v192, -8, v0
	s_add_u32 s8, s18, s24
	s_addc_u32 s9, s19, s25
	s_mov_b64 s[50:51], vcc
	s_mov_b64 vcc, s[40:41]
	v_cndmask_b32_dpp v188, v163, v162, vcc quad_perm:[1,0,3,2] row_mask:0xf bank_mask:0xf
	v_cndmask_b32_dpp v190, v161, v160, vcc quad_perm:[1,0,3,2] row_mask:0xf bank_mask:0xf
	s_mov_b64 vcc, s[42:43]
	v_cndmask_b32_dpp v189, v162, v163, vcc quad_perm:[1,0,3,2] row_mask:0xf bank_mask:0xf
	v_cndmask_b32_dpp v191, v160, v161, vcc quad_perm:[1,0,3,2] row_mask:0xf bank_mask:0xf
	s_mov_b64 vcc, s[46:47]
	v_cndmask_b32_dpp v162, v190, v188, vcc quad_perm:[2,3,0,1] row_mask:0xf bank_mask:0xf
	v_cndmask_b32_dpp v163, v191, v189, vcc quad_perm:[2,3,0,1] row_mask:0xf bank_mask:0xf
	s_mov_b64 vcc, s[48:49]
	v_cndmask_b32_dpp v160, v188, v190, vcc quad_perm:[2,3,0,1] row_mask:0xf bank_mask:0xf
	v_cndmask_b32_dpp v161, v189, v191, vcc quad_perm:[2,3,0,1] row_mask:0xf bank_mask:0xf
	s_mov_b64 vcc, s[50:51]
	v_lshl_add_u32 v192, v158, 9, v192
	v_cvt_pk_bf16_f32 v161, v160, v161
	v_cvt_pk_bf16_f32 v160, v162, v163
	v_add_u32_e32 v192, v192, v226
	v_mov_b32_e32 v193, v1
	v_lshl_add_u64 v[192:193], s[8:9], 0, v[192:193]
	global_store_dwordx2 v[192:193], v[160:161], off

; __device__ __forceinline__ bf16_t f2bf(float x) { return (bf16_t)(cvt_pk_bf16(x, 0.f) & 0xffffu); }
; __device__ __forceinline__ void st_bf4(bf16_t* p, f32x4 v) { u32x2 w; w.x = cvt_pk_bf16(v[0], v[1]); w.y = cvt_pk_bf16(v[2], v[3]); *(u32x2*)p = w; }
;     __device__ __forceinline__ void operator()(const Acc& acc, const Unit& u, int wr, int wc, int fr, int fq) const {
;     ...
;                     for (int n = 0; n < 2; ++n) { const int col = col0 + bj * 128 + n * 16; const f32x4 v = acc[ai][bj][m][n] * rs;
;                         if (col < 512) st_bf4(Kb + (size_t)row * 512 + col, v);
;                         else {
; #pragma unroll
;                             for (int j = 0; j < 4; ++j) Vt[((size_t)(row >> 8) * 512 + (col - 512 + j)) * 256 + (row & 255)] = f2bf(v[j]); } } }
.LBB0_558:
	s_or_b64 exec, exec, s[6:7]
	v_or_b32_e32 v123, 0x80, v146
	v_mov_b32_e32 v160, v164
	v_mov_b32_e32 v161, v164
	v_pk_mul_f32 v[166:167], v[120:121], v[160:161]
	v_pk_mul_f32 v[170:171], v[118:119], v[164:165]
	v_cmp_lt_i32_e64 s[6:7], s59, v123
	v_add_u32_e32 v162, 0xfffffe80, v146
	v_add_u32_e32 v160, 0xfffffe81, v146
	v_add_u32_e32 v120, 0xfffffe82, v146
	v_add_u32_e32 v118, 0xfffffe83, v146
	s_and_saveexec_b64 s[8:9], s[6:7]
	s_xor_b64 s[8:9], exec, s[8:9]
	s_cbranch_execz .LBB0_560
	v_and_b32_e32 v192, -8, v0
	s_add_u32 s26, s18, s24
	s_addc_u32 s27, s19, s25
	s_mov_b64 s[50:51], vcc
	s_mov_b64 vcc, s[40:41]
	v_cndmask_b32_dpp v188, v171, v170, vcc quad_perm:[1,0,3,2] row_mask:0xf bank_mask:0xf
	v_cndmask_b32_dpp v190, v167, v166, vcc quad_perm:[1,0,3,2] row_mask:0xf bank_mask:0xf
	s_mov_b64 vcc, s[42:43]
	v_cndmask_b32_dpp v189, v170, v171, vcc quad_perm:[1,0,3,2] row_mask:0xf bank_mask:0xf
	v_cndmask_b32_dpp v191, v166, v167, vcc quad_perm:[1,0,3,2] row_mask:0xf bank_mask:0xf
	s_mov_b64 vcc, s[46:47]
	v_cndmask_b32_dpp v170, v190, v188, vcc quad_perm:[2,3,0,1] row_mask:0xf bank_mask:0xf
	v_cndmask_b32_dpp v171, v191, v189, vcc quad_perm:[2,3,0,1] row_mask:0xf bank_mask:0xf
	s_mov_b64 vcc, s[48:49]
	v_cndmask_b32_dpp v166, v188, v190, vcc quad_perm:[2,3,0,1] row_mask:0xf bank_mask:0xf
	v_cndmask_b32_dpp v167, v189, v191, vcc quad_perm:[2,3,0,1] row_mask:0xf bank_mask:0xf
	s_mov_b64 vcc, s[50:51]
	v_lshl_add_u32 v192, v162, 9, v192
	v_cvt_pk_bf16_f32 v167, v166, v167
	v_cvt_pk_bf16_f32 v166, v170, v171
	v_add_u32_e32 v192, v192, v226
	v_mov_b32_e32 v193, v1
	v_lshl_add_u64 v[192:193], s[26:27], 0, v[192:193]
	global_store_dwordx2 v[192:193], v[166:167], off

; __device__ __forceinline__ bf16_t f2bf(float x) { return (bf16_t)(cvt_pk_bf16(x, 0.f) & 0xffffu); }
; __device__ __forceinline__ void st_bf4(bf16_t* p, f32x4 v) { u32x2 w; w.x = cvt_pk_bf16(v[0], v[1]); w.y = cvt_pk_bf16(v[2], v[3]); *(u32x2*)p = w; }
;     __device__ __forceinline__ void operator()(const Acc& acc, const Unit& u, int wr, int wc, int fr, int fq) const {
;     ...
;                     for (int n = 0; n < 2; ++n) { const int col = col0 + bj * 128 + n * 16; const f32x4 v = acc[ai][bj][m][n] * rs;
;                         if (col < 512) st_bf4(Kb + (size_t)row * 512 + col, v);
;                         else {
; #pragma unroll
;                             for (int j = 0; j < 4; ++j) Vt[((size_t)(row >> 8) * 512 + (col - 512 + j)) * 256 + (row & 255)] = f2bf(v[j]); } } }
.LBB0_562:
	s_or_b64 exec, exec, s[8:9]
	v_or_b32_e32 v119, 0x90, v146
	v_mov_b32_e32 v166, v164
	v_mov_b32_e32 v167, v164
	v_pk_mul_f32 v[170:171], v[116:117], v[166:167]
	v_pk_mul_f32 v[172:173], v[114:115], v[164:165]
	v_cmp_lt_i32_e64 s[8:9], s59, v119
	v_add_u32_e32 v166, 0xfffffe90, v146
	v_add_u32_e32 v164, 0xfffffe91, v146
	v_add_u32_e32 v116, 0xfffffe92, v146
	v_add_u32_e32 v114, 0xfffffe93, v146
	s_and_saveexec_b64 s[26:27], s[8:9]
	s_xor_b64 s[26:27], exec, s[26:27]
	s_cbranch_execz .LBB0_564
	v_and_b32_e32 v192, -8, v0
	s_add_u32 s72, s18, s24
	s_addc_u32 s73, s19, s25
	s_mov_b64 s[50:51], vcc
	s_mov_b64 vcc, s[40:41]
	v_cndmask_b32_dpp v188, v173, v172, vcc quad_perm:[1,0,3,2] row_mask:0xf bank_mask:0xf
	v_cndmask_b32_dpp v190, v171, v170, vcc quad_perm:[1,0,3,2] row_mask:0xf bank_mask:0xf
	s_mov_b64 vcc, s[42:43]
	v_cndmask_b32_dpp v189, v172, v173, vcc quad_perm:[1,0,3,2] row_mask:0xf bank_mask:0xf
	v_cndmask_b32_dpp v191, v170, v171, vcc quad_perm:[1,0,3,2] row_mask:0xf bank_mask:0xf
	s_mov_b64 vcc, s[46:47]
	v_cndmask_b32_dpp v172, v190, v188, vcc quad_perm:[2,3,0,1] row_mask:0xf bank_mask:0xf
	v_cndmask_b32_dpp v173, v191, v189, vcc quad_perm:[2,3,0,1] row_mask:0xf bank_mask:0xf
	s_mov_b64 vcc, s[48:49]
	v_cndmask_b32_dpp v170, v188, v190, vcc quad_perm:[2,3,0,1] row_mask:0xf bank_mask:0xf
	v_cndmask_b32_dpp v171, v189, v191, vcc quad_perm:[2,3,0,1] row_mask:0xf bank_mask:0xf
	s_mov_b64 vcc, s[50:51]
	v_lshl_add_u32 v192, v166, 9, v192
	v_cvt_pk_bf16_f32 v171, v170, v171
	v_cvt_pk_bf16_f32 v170, v172, v173
	v_add_u32_e32 v192, v192, v226
	v_mov_b32_e32 v193, v1
	v_lshl_add_u64 v[192:193], s[72:73], 0, v[192:193]
	global_store_dwordx2 v[192:193], v[170:171], off

;     __device__ __forceinline__ void operator()(const Acc& acc, const Unit& u, int wr, int wc, int fr, int fq) const {
;     ...
;             for (int m = 0; m < 4; ++m) { const int row = row0 + ai * 128 + m * 16; const float rs = rstd[row];
.LBB0_566:
	s_or_b64 exec, exec, s[26:27]
	v_mov_b32_e32 v168, v194
	s_movk_i32 s26, 0xdf
	v_bitop3_b32 v0, v148, s26, 16 bitop3:0xc8
	v_lshlrev_b32_e32 v0, 1, v0

; __device__ __forceinline__ bf16_t f2bf(float x) { return (bf16_t)(cvt_pk_bf16(x, 0.f) & 0xffffu); }
; __device__ __forceinline__ void st_bf4(bf16_t* p, f32x4 v) { u32x2 w; w.x = cvt_pk_bf16(v[0], v[1]); w.y = cvt_pk_bf16(v[2], v[3]); *(u32x2*)p = w; }
;     __device__ __forceinline__ void operator()(const Acc& acc, const Unit& u, int wr, int wc, int fr, int fq) const {
;     ...
;                     for (int n = 0; n < 2; ++n) { const int col = col0 + bj * 128 + n * 16; const f32x4 v = acc[ai][bj][m][n] * rs;
;                         if (col < 512) st_bf4(Kb + (size_t)row * 512 + col, v);
;                         else {
; #pragma unroll
;                             for (int j = 0; j < 4; ++j) Vt[((size_t)(row >> 8) * 512 + (col - 512 + j)) * 256 + (row & 255)] = f2bf(v[j]); } } }
	v_pk_mul_f32 v[112:113], v[112:113], v[168:169] op_sel_hi:[1,0]
	v_pk_mul_f32 v[170:171], v[110:111], v[168:169] op_sel_hi:[1,0]
	s_and_saveexec_b64 s[26:27], vcc
	s_xor_b64 s[26:27], exec, s[26:27]
	s_cbranch_execz .LBB0_568
	v_and_b32_e32 v192, -8, v0
	s_add_u32 s72, s18, s24
	s_addc_u32 s73, s19, s25
	s_mov_b64 s[50:51], vcc
	s_mov_b64 vcc, s[40:41]
	v_cndmask_b32_dpp v188, v171, v170, vcc quad_perm:[1,0,3,2] row_mask:0xf bank_mask:0xf
	v_cndmask_b32_dpp v190, v113, v112, vcc quad_perm:[1,0,3,2] row_mask:0xf bank_mask:0xf
	s_mov_b64 vcc, s[42:43]
	v_cndmask_b32_dpp v189, v170, v171, vcc quad_perm:[1,0,3,2] row_mask:0xf bank_mask:0xf
	v_cndmask_b32_dpp v191, v112, v113, vcc quad_perm:[1,0,3,2] row_mask:0xf bank_mask:0xf
	s_mov_b64 vcc, s[46:47]
	v_cndmask_b32_dpp v170, v190, v188, vcc quad_perm:[2,3,0,1] row_mask:0xf bank_mask:0xf
	v_cndmask_b32_dpp v171, v191, v189, vcc quad_perm:[2,3,0,1] row_mask:0xf bank_mask:0xf
	s_mov_b64 vcc, s[48:49]
	v_cndmask_b32_dpp v112, v188, v190, vcc quad_perm:[2,3,0,1] row_mask:0xf bank_mask:0xf
	v_cndmask_b32_dpp v113, v189, v191, vcc quad_perm:[2,3,0,1] row_mask:0xf bank_mask:0xf
	s_mov_b64 vcc, s[50:51]
	v_lshl_add_u32 v192, v154, 9, v192
	v_cvt_pk_bf16_f32 v113, v112, v113
	v_cvt_pk_bf16_f32 v112, v170, v171
	v_add_u32_e32 v192, v192, v226
	v_mov_b32_e32 v193, v1
	v_lshl_add_u64 v[192:193], s[72:73], 0, v[192:193]
	global_store_dwordx2 v[192:193], v[112:113], off

; __device__ __forceinline__ bf16_t f2bf(float x) { return (bf16_t)(cvt_pk_bf16(x, 0.f) & 0xffffu); }
; __device__ __forceinline__ void st_bf4(bf16_t* p, f32x4 v) { u32x2 w; w.x = cvt_pk_bf16(v[0], v[1]); w.y = cvt_pk_bf16(v[2], v[3]); *(u32x2*)p = w; }
;     __device__ __forceinline__ void operator()(const Acc& acc, const Unit& u, int wr, int wc, int fr, int fq) const {
;     ...
;                     for (int n = 0; n < 2; ++n) { const int col = col0 + bj * 128 + n * 16; const f32x4 v = acc[ai][bj][m][n] * rs;
;                         if (col < 512) st_bf4(Kb + (size_t)row * 512 + col, v);
;                         else {
; #pragma unroll
;                             for (int j = 0; j < 4; ++j) Vt[((size_t)(row >> 8) * 512 + (col - 512 + j)) * 256 + (row & 255)] = f2bf(v[j]); } } }
.LBB0_570:
	s_or_b64 exec, exec, s[26:27]
	v_mov_b32_e32 v169, v168
	v_mov_b32_e32 v112, v168
	v_mov_b32_e32 v113, v168
	v_pk_mul_f32 v[108:109], v[108:109], v[112:113]
	v_pk_mul_f32 v[106:107], v[106:107], v[168:169]
	s_and_saveexec_b64 s[26:27], s[4:5]
	s_xor_b64 s[26:27], exec, s[26:27]
	s_cbranch_execz .LBB0_572
	v_and_b32_e32 v192, -8, v0
	s_add_u32 s72, s18, s24
	s_addc_u32 s73, s19, s25
	s_mov_b64 s[50:51], vcc
	s_mov_b64 vcc, s[40:41]
	v_cndmask_b32_dpp v188, v107, v106, vcc quad_perm:[1,0,3,2] row_mask:0xf bank_mask:0xf
	v_cndmask_b32_dpp v190, v109, v108, vcc quad_perm:[1,0,3,2] row_mask:0xf bank_mask:0xf
	s_mov_b64 vcc, s[42:43]
	v_cndmask_b32_dpp v189, v106, v107, vcc quad_perm:[1,0,3,2] row_mask:0xf bank_mask:0xf
	v_cndmask_b32_dpp v191, v108, v109, vcc quad_perm:[1,0,3,2] row_mask:0xf bank_mask:0xf
	s_mov_b64 vcc, s[46:47]
	v_cndmask_b32_dpp v106, v190, v188, vcc quad_perm:[2,3,0,1] row_mask:0xf bank_mask:0xf
	v_cndmask_b32_dpp v107, v191, v189, vcc quad_perm:[2,3,0,1] row_mask:0xf bank_mask:0xf
	s_mov_b64 vcc, s[48:49]
	v_cndmask_b32_dpp v108, v188, v190, vcc quad_perm:[2,3,0,1] row_mask:0xf bank_mask:0xf
	v_cndmask_b32_dpp v109, v189, v191, vcc quad_perm:[2,3,0,1] row_mask:0xf bank_mask:0xf
	s_mov_b64 vcc, s[50:51]
	v_lshl_add_u32 v192, v158, 9, v192
	v_cvt_pk_bf16_f32 v109, v108, v109
	v_cvt_pk_bf16_f32 v108, v106, v107
	v_add_u32_e32 v192, v192, v226
	v_mov_b32_e32 v193, v1
	v_lshl_add_u64 v[192:193], s[72:73], 0, v[192:193]
	global_store_dwordx2 v[192:193], v[108:109], off

; __device__ __forceinline__ bf16_t f2bf(float x) { return (bf16_t)(cvt_pk_bf16(x, 0.f) & 0xffffu); }
; __device__ __forceinline__ void st_bf4(bf16_t* p, f32x4 v) { u32x2 w; w.x = cvt_pk_bf16(v[0], v[1]); w.y = cvt_pk_bf16(v[2], v[3]); *(u32x2*)p = w; }
;     __device__ __forceinline__ void operator()(const Acc& acc, const Unit& u, int wr, int wc, int fr, int fq) const {
;     ...
;                     for (int n = 0; n < 2; ++n) { const int col = col0 + bj * 128 + n * 16; const f32x4 v = acc[ai][bj][m][n] * rs;
;                         if (col < 512) st_bf4(Kb + (size_t)row * 512 + col, v);
;                         else {
; #pragma unroll
;                             for (int j = 0; j < 4; ++j) Vt[((size_t)(row >> 8) * 512 + (col - 512 + j)) * 256 + (row & 255)] = f2bf(v[j]); } } }
.LBB0_574:
	s_or_b64 exec, exec, s[26:27]
	v_mov_b32_e32 v106, v168
	v_mov_b32_e32 v107, v168
	v_pk_mul_f32 v[104:105], v[104:105], v[106:107]
	v_pk_mul_f32 v[102:103], v[102:103], v[168:169]
	s_and_saveexec_b64 s[26:27], s[6:7]
	s_xor_b64 s[26:27], exec, s[26:27]
	s_cbranch_execz .LBB0_576
	v_and_b32_e32 v192, -8, v0
	s_add_u32 s72, s18, s24
	s_addc_u32 s73, s19, s25
	s_mov_b64 s[50:51], vcc
	s_mov_b64 vcc, s[40:41]
	v_cndmask_b32_dpp v188, v103, v102, vcc quad_perm:[1,0,3,2] row_mask:0xf bank_mask:0xf
	v_cndmask_b32_dpp v190, v105, v104, vcc quad_perm:[1,0,3,2] row_mask:0xf bank_mask:0xf
	s_mov_b64 vcc, s[42:43]
	v_cndmask_b32_dpp v189, v102, v103, vcc quad_perm:[1,0,3,2] row_mask:0xf bank_mask:0xf
	v_cndmask_b32_dpp v191, v104, v105, vcc quad_perm:[1,0,3,2] row_mask:0xf bank_mask:0xf
	s_mov_b64 vcc, s[46:47]
	v_cndmask_b32_dpp v102, v190, v188, vcc quad_perm:[2,3,0,1] row_mask:0xf bank_mask:0xf
	v_cndmask_b32_dpp v103, v191, v189, vcc quad_perm:[2,3,0,1] row_mask:0xf bank_mask:0xf
	s_mov_b64 vcc, s[48:49]
	v_cndmask_b32_dpp v104, v188, v190, vcc quad_perm:[2,3,0,1] row_mask:0xf bank_mask:0xf
	v_cndmask_b32_dpp v105, v189, v191, vcc quad_perm:[2,3,0,1] row_mask:0xf bank_mask:0xf
	s_mov_b64 vcc, s[50:51]
	v_lshl_add_u32 v192, v162, 9, v192
	v_cvt_pk_bf16_f32 v105, v104, v105
	v_cvt_pk_bf16_f32 v104, v102, v103
	v_add_u32_e32 v192, v192, v226
	v_mov_b32_e32 v193, v1
	v_lshl_add_u64 v[192:193], s[72:73], 0, v[192:193]
	global_store_dwordx2 v[192:193], v[104:105], off

; __device__ __forceinline__ bf16_t f2bf(float x) { return (bf16_t)(cvt_pk_bf16(x, 0.f) & 0xffffu); }
; __device__ __forceinline__ void st_bf4(bf16_t* p, f32x4 v) { u32x2 w; w.x = cvt_pk_bf16(v[0], v[1]); w.y = cvt_pk_bf16(v[2], v[3]); *(u32x2*)p = w; }
;     __device__ __forceinline__ void operator()(const Acc& acc, const Unit& u, int wr, int wc, int fr, int fq) const {
;     ...
;                     for (int n = 0; n < 2; ++n) { const int col = col0 + bj * 128 + n * 16; const f32x4 v = acc[ai][bj][m][n] * rs;
;                         if (col < 512) st_bf4(Kb + (size_t)row * 512 + col, v);
;                         else {
; #pragma unroll
;                             for (int j = 0; j < 4; ++j) Vt[((size_t)(row >> 8) * 512 + (col - 512 + j)) * 256 + (row & 255)] = f2bf(v[j]); } } }
.LBB0_578:
	s_or_b64 exec, exec, s[26:27]
	v_mov_b32_e32 v102, v168
	v_mov_b32_e32 v103, v168
	v_pk_mul_f32 v[100:101], v[100:101], v[102:103]
	v_pk_mul_f32 v[98:99], v[98:99], v[168:169]
	s_and_saveexec_b64 s[26:27], s[8:9]
	s_xor_b64 s[26:27], exec, s[26:27]
	s_cbranch_execz .LBB0_580
	v_and_b32_e32 v192, -8, v0
	s_add_u32 s72, s18, s24
	s_addc_u32 s73, s19, s25
	s_mov_b64 s[50:51], vcc
	s_mov_b64 vcc, s[40:41]
	v_cndmask_b32_dpp v188, v99, v98, vcc quad_perm:[1,0,3,2] row_mask:0xf bank_mask:0xf
	v_cndmask_b32_dpp v190, v101, v100, vcc quad_perm:[1,0,3,2] row_mask:0xf bank_mask:0xf
	s_mov_b64 vcc, s[42:43]
	v_cndmask_b32_dpp v189, v98, v99, vcc quad_perm:[1,0,3,2] row_mask:0xf bank_mask:0xf
	v_cndmask_b32_dpp v191, v100, v101, vcc quad_perm:[1,0,3,2] row_mask:0xf bank_mask:0xf
	s_mov_b64 vcc, s[46:47]
	v_cndmask_b32_dpp v98, v190, v188, vcc quad_perm:[2,3,0,1] row_mask:0xf bank_mask:0xf
	v_cndmask_b32_dpp v99, v191, v189, vcc quad_perm:[2,3,0,1] row_mask:0xf bank_mask:0xf
	s_mov_b64 vcc, s[48:49]
	v_cndmask_b32_dpp v100, v188, v190, vcc quad_perm:[2,3,0,1] row_mask:0xf bank_mask:0xf
	v_cndmask_b32_dpp v101, v189, v191, vcc quad_perm:[2,3,0,1] row_mask:0xf bank_mask:0xf
	s_mov_b64 vcc, s[50:51]
	v_lshl_add_u32 v192, v166, 9, v192
	v_cvt_pk_bf16_f32 v101, v100, v101
	v_cvt_pk_bf16_f32 v100, v98, v99
	v_add_u32_e32 v192, v192, v226
	v_mov_b32_e32 v193, v1
	v_lshl_add_u64 v[192:193], s[72:73], 0, v[192:193]
	global_store_dwordx2 v[192:193], v[100:101], off

;     __device__ __forceinline__ void operator()(const Acc& acc, const Unit& u, int wr, int wc, int fr, int fq) const {
;     ...
;             for (int m = 0; m < 4; ++m) { const int row = row0 + ai * 128 + m * 16; const float rs = rstd[row];
.LBB0_582:
	s_or_b64 exec, exec, s[26:27]
	v_mov_b32_e32 v98, v195
	s_movk_i32 s26, 0xef
	v_bitop3_b32 v0, v148, s26, 32 bitop3:0xc8
	v_lshlrev_b32_e32 v0, 1, v0

; __device__ __forceinline__ bf16_t f2bf(float x) { return (bf16_t)(cvt_pk_bf16(x, 0.f) & 0xffffu); }
; __device__ __forceinline__ void st_bf4(bf16_t* p, f32x4 v) { u32x2 w; w.x = cvt_pk_bf16(v[0], v[1]); w.y = cvt_pk_bf16(v[2], v[3]); *(u32x2*)p = w; }
;     __device__ __forceinline__ void operator()(const Acc& acc, const Unit& u, int wr, int wc, int fr, int fq) const {
;     ...
;                     for (int n = 0; n < 2; ++n) { const int col = col0 + bj * 128 + n * 16; const f32x4 v = acc[ai][bj][m][n] * rs;
;                         if (col < 512) st_bf4(Kb + (size_t)row * 512 + col, v);
;                         else {
; #pragma unroll
;                             for (int j = 0; j < 4; ++j) Vt[((size_t)(row >> 8) * 512 + (col - 512 + j)) * 256 + (row & 255)] = f2bf(v[j]); } } }
	v_pk_mul_f32 v[96:97], v[96:97], v[98:99] op_sel_hi:[1,0]
	v_pk_mul_f32 v[100:101], v[94:95], v[98:99] op_sel_hi:[1,0]
	s_and_saveexec_b64 s[26:27], vcc
	s_xor_b64 s[26:27], exec, s[26:27]
	s_cbranch_execz .LBB0_584
	v_and_b32_e32 v192, -8, v0
	s_add_u32 s72, s18, s24
	s_addc_u32 s73, s19, s25
	s_mov_b64 s[50:51], vcc
	s_mov_b64 vcc, s[40:41]
	v_cndmask_b32_dpp v188, v101, v100, vcc quad_perm:[1,0,3,2] row_mask:0xf bank_mask:0xf
	v_cndmask_b32_dpp v190, v97, v96, vcc quad_perm:[1,0,3,2] row_mask:0xf bank_mask:0xf
	s_mov_b64 vcc, s[42:43]
	v_cndmask_b32_dpp v189, v100, v101, vcc quad_perm:[1,0,3,2] row_mask:0xf bank_mask:0xf
	v_cndmask_b32_dpp v191, v96, v97, vcc quad_perm:[1,0,3,2] row_mask:0xf bank_mask:0xf
	s_mov_b64 vcc, s[46:47]
	v_cndmask_b32_dpp v100, v190, v188, vcc quad_perm:[2,3,0,1] row_mask:0xf bank_mask:0xf
	v_cndmask_b32_dpp v101, v191, v189, vcc quad_perm:[2,3,0,1] row_mask:0xf bank_mask:0xf
	s_mov_b64 vcc, s[48:49]
	v_cndmask_b32_dpp v96, v188, v190, vcc quad_perm:[2,3,0,1] row_mask:0xf bank_mask:0xf
	v_cndmask_b32_dpp v97, v189, v191, vcc quad_perm:[2,3,0,1] row_mask:0xf bank_mask:0xf
	s_mov_b64 vcc, s[50:51]
	v_lshl_add_u32 v192, v154, 9, v192
	v_cvt_pk_bf16_f32 v97, v96, v97
	v_cvt_pk_bf16_f32 v96, v100, v101
	v_add_u32_e32 v192, v192, v226
	v_mov_b32_e32 v193, v1
	v_lshl_add_u64 v[192:193], s[72:73], 0, v[192:193]
	global_store_dwordx2 v[192:193], v[96:97], off

; __device__ __forceinline__ bf16_t f2bf(float x) { return (bf16_t)(cvt_pk_bf16(x, 0.f) & 0xffffu); }
; __device__ __forceinline__ void st_bf4(bf16_t* p, f32x4 v) { u32x2 w; w.x = cvt_pk_bf16(v[0], v[1]); w.y = cvt_pk_bf16(v[2], v[3]); *(u32x2*)p = w; }
;     __device__ __forceinline__ void operator()(const Acc& acc, const Unit& u, int wr, int wc, int fr, int fq) const {
;     ...
;                     for (int n = 0; n < 2; ++n) { const int col = col0 + bj * 128 + n * 16; const f32x4 v = acc[ai][bj][m][n] * rs;
;                         if (col < 512) st_bf4(Kb + (size_t)row * 512 + col, v);
;                         else {
; #pragma unroll
;                             for (int j = 0; j < 4; ++j) Vt[((size_t)(row >> 8) * 512 + (col - 512 + j)) * 256 + (row & 255)] = f2bf(v[j]); } } }
.LBB0_586:
	s_or_b64 exec, exec, s[26:27]
	v_mov_b32_e32 v99, v98
	v_mov_b32_e32 v96, v98
	v_mov_b32_e32 v97, v98
	v_pk_mul_f32 v[92:93], v[92:93], v[96:97]
	v_pk_mul_f32 v[90:91], v[90:91], v[98:99]
	s_and_saveexec_b64 s[26:27], s[4:5]
	s_xor_b64 s[26:27], exec, s[26:27]
	s_cbranch_execz .LBB0_588
	v_and_b32_e32 v192, -8, v0
	s_add_u32 s72, s18, s24
	s_addc_u32 s73, s19, s25
	s_mov_b64 s[50:51], vcc
	s_mov_b64 vcc, s[40:41]
	v_cndmask_b32_dpp v188, v91, v90, vcc quad_perm:[1,0,3,2] row_mask:0xf bank_mask:0xf
	v_cndmask_b32_dpp v190, v93, v92, vcc quad_perm:[1,0,3,2] row_mask:0xf bank_mask:0xf
	s_mov_b64 vcc, s[42:43]
	v_cndmask_b32_dpp v189, v90, v91, vcc quad_perm:[1,0,3,2] row_mask:0xf bank_mask:0xf
	v_cndmask_b32_dpp v191, v92, v93, vcc quad_perm:[1,0,3,2] row_mask:0xf bank_mask:0xf
	s_mov_b64 vcc, s[46:47]
	v_cndmask_b32_dpp v90, v190, v188, vcc quad_perm:[2,3,0,1] row_mask:0xf bank_mask:0xf
	v_cndmask_b32_dpp v91, v191, v189, vcc quad_perm:[2,3,0,1] row_mask:0xf bank_mask:0xf
	s_mov_b64 vcc, s[48:49]
	v_cndmask_b32_dpp v92, v188, v190, vcc quad_perm:[2,3,0,1] row_mask:0xf bank_mask:0xf
	v_cndmask_b32_dpp v93, v189, v191, vcc quad_perm:[2,3,0,1] row_mask:0xf bank_mask:0xf
	s_mov_b64 vcc, s[50:51]
	v_lshl_add_u32 v192, v158, 9, v192
	v_cvt_pk_bf16_f32 v93, v92, v93
	v_cvt_pk_bf16_f32 v92, v90, v91
	v_add_u32_e32 v192, v192, v226
	v_mov_b32_e32 v193, v1
	v_lshl_add_u64 v[192:193], s[72:73], 0, v[192:193]
	global_store_dwordx2 v[192:193], v[92:93], off

; __device__ __forceinline__ bf16_t f2bf(float x) { return (bf16_t)(cvt_pk_bf16(x, 0.f) & 0xffffu); }
; __device__ __forceinline__ void st_bf4(bf16_t* p, f32x4 v) { u32x2 w; w.x = cvt_pk_bf16(v[0], v[1]); w.y = cvt_pk_bf16(v[2], v[3]); *(u32x2*)p = w; }
;     __device__ __forceinline__ void operator()(const Acc& acc, const Unit& u, int wr, int wc, int fr, int fq) const {
;     ...
;                     for (int n = 0; n < 2; ++n) { const int col = col0 + bj * 128 + n * 16; const f32x4 v = acc[ai][bj][m][n] * rs;
;                         if (col < 512) st_bf4(Kb + (size_t)row * 512 + col, v);
;                         else {
; #pragma unroll
;                             for (int j = 0; j < 4; ++j) Vt[((size_t)(row >> 8) * 512 + (col - 512 + j)) * 256 + (row & 255)] = f2bf(v[j]); } } }
.LBB0_590:
	s_or_b64 exec, exec, s[26:27]
	v_mov_b32_e32 v90, v98
	v_mov_b32_e32 v91, v98
	v_pk_mul_f32 v[88:89], v[88:89], v[90:91]
	v_pk_mul_f32 v[86:87], v[86:87], v[98:99]
	s_and_saveexec_b64 s[26:27], s[6:7]
	s_xor_b64 s[26:27], exec, s[26:27]
	s_cbranch_execz .LBB0_592
	v_and_b32_e32 v192, -8, v0
	s_add_u32 s72, s18, s24
	s_addc_u32 s73, s19, s25
	s_mov_b64 s[50:51], vcc
	s_mov_b64 vcc, s[40:41]
	v_cndmask_b32_dpp v188, v87, v86, vcc quad_perm:[1,0,3,2] row_mask:0xf bank_mask:0xf
	v_cndmask_b32_dpp v190, v89, v88, vcc quad_perm:[1,0,3,2] row_mask:0xf bank_mask:0xf
	s_mov_b64 vcc, s[42:43]
	v_cndmask_b32_dpp v189, v86, v87, vcc quad_perm:[1,0,3,2] row_mask:0xf bank_mask:0xf
	v_cndmask_b32_dpp v191, v88, v89, vcc quad_perm:[1,0,3,2] row_mask:0xf bank_mask:0xf
	s_mov_b64 vcc, s[46:47]
	v_cndmask_b32_dpp v86, v190, v188, vcc quad_perm:[2,3,0,1] row_mask:0xf bank_mask:0xf
	v_cndmask_b32_dpp v87, v191, v189, vcc quad_perm:[2,3,0,1] row_mask:0xf bank_mask:0xf
	s_mov_b64 vcc, s[48:49]
	v_cndmask_b32_dpp v88, v188, v190, vcc quad_perm:[2,3,0,1] row_mask:0xf bank_mask:0xf
	v_cndmask_b32_dpp v89, v189, v191, vcc quad_perm:[2,3,0,1] row_mask:0xf bank_mask:0xf
	s_mov_b64 vcc, s[50:51]
	v_lshl_add_u32 v192, v162, 9, v192
	v_cvt_pk_bf16_f32 v89, v88, v89
	v_cvt_pk_bf16_f32 v88, v86, v87
	v_add_u32_e32 v192, v192, v226
	v_mov_b32_e32 v193, v1
	v_lshl_add_u64 v[192:193], s[72:73], 0, v[192:193]
	global_store_dwordx2 v[192:193], v[88:89], off

; __device__ __forceinline__ bf16_t f2bf(float x) { return (bf16_t)(cvt_pk_bf16(x, 0.f) & 0xffffu); }
; __device__ __forceinline__ void st_bf4(bf16_t* p, f32x4 v) { u32x2 w; w.x = cvt_pk_bf16(v[0], v[1]); w.y = cvt_pk_bf16(v[2], v[3]); *(u32x2*)p = w; }
;     __device__ __forceinline__ void operator()(const Acc& acc, const Unit& u, int wr, int wc, int fr, int fq) const {
;     ...
;                     for (int n = 0; n < 2; ++n) { const int col = col0 + bj * 128 + n * 16; const f32x4 v = acc[ai][bj][m][n] * rs;
;                         if (col < 512) st_bf4(Kb + (size_t)row * 512 + col, v);
;                         else {
; #pragma unroll
;                             for (int j = 0; j < 4; ++j) Vt[((size_t)(row >> 8) * 512 + (col - 512 + j)) * 256 + (row & 255)] = f2bf(v[j]); } } }
.LBB0_594:
	s_or_b64 exec, exec, s[26:27]
	v_mov_b32_e32 v86, v98
	v_mov_b32_e32 v87, v98
	v_pk_mul_f32 v[84:85], v[84:85], v[86:87]
	v_pk_mul_f32 v[82:83], v[82:83], v[98:99]
	s_and_saveexec_b64 s[26:27], s[8:9]
	s_xor_b64 s[26:27], exec, s[26:27]
	s_cbranch_execz .LBB0_596
	v_and_b32_e32 v192, -8, v0
	s_add_u32 s72, s18, s24
	s_addc_u32 s73, s19, s25
	s_mov_b64 s[50:51], vcc
	s_mov_b64 vcc, s[40:41]
	v_cndmask_b32_dpp v188, v83, v82, vcc quad_perm:[1,0,3,2] row_mask:0xf bank_mask:0xf
	v_cndmask_b32_dpp v190, v85, v84, vcc quad_perm:[1,0,3,2] row_mask:0xf bank_mask:0xf
	s_mov_b64 vcc, s[42:43]
	v_cndmask_b32_dpp v189, v82, v83, vcc quad_perm:[1,0,3,2] row_mask:0xf bank_mask:0xf
	v_cndmask_b32_dpp v191, v84, v85, vcc quad_perm:[1,0,3,2] row_mask:0xf bank_mask:0xf
	s_mov_b64 vcc, s[46:47]
	v_cndmask_b32_dpp v82, v190, v188, vcc quad_perm:[2,3,0,1] row_mask:0xf bank_mask:0xf
	v_cndmask_b32_dpp v83, v191, v189, vcc quad_perm:[2,3,0,1] row_mask:0xf bank_mask:0xf
	s_mov_b64 vcc, s[48:49]
	v_cndmask_b32_dpp v84, v188, v190, vcc quad_perm:[2,3,0,1] row_mask:0xf bank_mask:0xf
	v_cndmask_b32_dpp v85, v189, v191, vcc quad_perm:[2,3,0,1] row_mask:0xf bank_mask:0xf
	s_mov_b64 vcc, s[50:51]
	v_lshl_add_u32 v192, v166, 9, v192
	v_cvt_pk_bf16_f32 v85, v84, v85
	v_cvt_pk_bf16_f32 v84, v82, v83
	v_add_u32_e32 v192, v192, v226
	v_mov_b32_e32 v193, v1
	v_lshl_add_u64 v[192:193], s[72:73], 0, v[192:193]
	global_store_dwordx2 v[192:193], v[84:85], off

;     __device__ __forceinline__ void operator()(const Acc& acc, const Unit& u, int wr, int wc, int fr, int fq) const {
;     ...
;             for (int m = 0; m < 4; ++m) { const int row = row0 + ai * 128 + m * 16; const float rs = rstd[row];
.LBB0_598:
	s_or_b64 exec, exec, s[26:27]
	v_mov_b32_e32 v82, v196
	s_movk_i32 s26, 0xff
	v_bitop3_b32 v0, v148, s26, 48 bitop3:0xc8
	v_lshlrev_b32_e32 v0, 1, v0

; __device__ __forceinline__ bf16_t f2bf(float x) { return (bf16_t)(cvt_pk_bf16(x, 0.f) & 0xffffu); }
; __device__ __forceinline__ void st_bf4(bf16_t* p, f32x4 v) { u32x2 w; w.x = cvt_pk_bf16(v[0], v[1]); w.y = cvt_pk_bf16(v[2], v[3]); *(u32x2*)p = w; }
;     __device__ __forceinline__ void operator()(const Acc& acc, const Unit& u, int wr, int wc, int fr, int fq) const {
;     ...
;                     for (int n = 0; n < 2; ++n) { const int col = col0 + bj * 128 + n * 16; const f32x4 v = acc[ai][bj][m][n] * rs;
;                         if (col < 512) st_bf4(Kb + (size_t)row * 512 + col, v);
;                         else {
; #pragma unroll
;                             for (int j = 0; j < 4; ++j) Vt[((size_t)(row >> 8) * 512 + (col - 512 + j)) * 256 + (row & 255)] = f2bf(v[j]); } } }
	v_pk_mul_f32 v[80:81], v[80:81], v[82:83] op_sel_hi:[1,0]
	v_pk_mul_f32 v[84:85], v[78:79], v[82:83] op_sel_hi:[1,0]
	s_and_saveexec_b64 s[26:27], vcc
	s_xor_b64 s[26:27], exec, s[26:27]
	s_cbranch_execz .LBB0_600
	v_and_b32_e32 v192, -8, v0
	s_add_u32 s72, s18, s24
	s_addc_u32 s73, s19, s25
	s_mov_b64 s[50:51], vcc
	s_mov_b64 vcc, s[40:41]
	v_cndmask_b32_dpp v188, v85, v84, vcc quad_perm:[1,0,3,2] row_mask:0xf bank_mask:0xf
	v_cndmask_b32_dpp v190, v81, v80, vcc quad_perm:[1,0,3,2] row_mask:0xf bank_mask:0xf
	s_mov_b64 vcc, s[42:43]
	v_cndmask_b32_dpp v189, v84, v85, vcc quad_perm:[1,0,3,2] row_mask:0xf bank_mask:0xf
	v_cndmask_b32_dpp v191, v80, v81, vcc quad_perm:[1,0,3,2] row_mask:0xf bank_mask:0xf
	s_mov_b64 vcc, s[46:47]
	v_cndmask_b32_dpp v84, v190, v188, vcc quad_perm:[2,3,0,1] row_mask:0xf bank_mask:0xf
	v_cndmask_b32_dpp v85, v191, v189, vcc quad_perm:[2,3,0,1] row_mask:0xf bank_mask:0xf
	s_mov_b64 vcc, s[48:49]
	v_cndmask_b32_dpp v80, v188, v190, vcc quad_perm:[2,3,0,1] row_mask:0xf bank_mask:0xf
	v_cndmask_b32_dpp v81, v189, v191, vcc quad_perm:[2,3,0,1] row_mask:0xf bank_mask:0xf
	s_mov_b64 vcc, s[50:51]
	v_lshl_add_u32 v192, v154, 9, v192
	v_cvt_pk_bf16_f32 v81, v80, v81
	v_cvt_pk_bf16_f32 v80, v84, v85
	v_add_u32_e32 v192, v192, v226
	v_mov_b32_e32 v193, v1
	v_lshl_add_u64 v[192:193], s[72:73], 0, v[192:193]
	global_store_dwordx2 v[192:193], v[80:81], off

; __device__ __forceinline__ bf16_t f2bf(float x) { return (bf16_t)(cvt_pk_bf16(x, 0.f) & 0xffffu); }
; __device__ __forceinline__ void st_bf4(bf16_t* p, f32x4 v) { u32x2 w; w.x = cvt_pk_bf16(v[0], v[1]); w.y = cvt_pk_bf16(v[2], v[3]); *(u32x2*)p = w; }
;     __device__ __forceinline__ void operator()(const Acc& acc, const Unit& u, int wr, int wc, int fr, int fq) const {
;     ...
;                     for (int n = 0; n < 2; ++n) { const int col = col0 + bj * 128 + n * 16; const f32x4 v = acc[ai][bj][m][n] * rs;
;                         if (col < 512) st_bf4(Kb + (size_t)row * 512 + col, v);
;                         else {
; #pragma unroll
;                             for (int j = 0; j < 4; ++j) Vt[((size_t)(row >> 8) * 512 + (col - 512 + j)) * 256 + (row & 255)] = f2bf(v[j]); } } }
.LBB0_602:
	s_or_b64 exec, exec, s[26:27]
	v_mov_b32_e32 v83, v82
	v_mov_b32_e32 v80, v82
	v_mov_b32_e32 v81, v82
	v_pk_mul_f32 v[76:77], v[76:77], v[80:81]
	v_pk_mul_f32 v[74:75], v[74:75], v[82:83]
	s_and_saveexec_b64 s[26:27], s[4:5]
	s_xor_b64 s[26:27], exec, s[26:27]
	s_cbranch_execz .LBB0_604
	v_and_b32_e32 v192, -8, v0
	s_add_u32 s72, s18, s24
	s_addc_u32 s73, s19, s25
	s_mov_b64 s[50:51], vcc
	s_mov_b64 vcc, s[40:41]
	v_cndmask_b32_dpp v188, v75, v74, vcc quad_perm:[1,0,3,2] row_mask:0xf bank_mask:0xf
	v_cndmask_b32_dpp v190, v77, v76, vcc quad_perm:[1,0,3,2] row_mask:0xf bank_mask:0xf
	s_mov_b64 vcc, s[42:43]
	v_cndmask_b32_dpp v189, v74, v75, vcc quad_perm:[1,0,3,2] row_mask:0xf bank_mask:0xf
	v_cndmask_b32_dpp v191, v76, v77, vcc quad_perm:[1,0,3,2] row_mask:0xf bank_mask:0xf
	s_mov_b64 vcc, s[46:47]
	v_cndmask_b32_dpp v74, v190, v188, vcc quad_perm:[2,3,0,1] row_mask:0xf bank_mask:0xf
	v_cndmask_b32_dpp v75, v191, v189, vcc quad_perm:[2,3,0,1] row_mask:0xf bank_mask:0xf
	s_mov_b64 vcc, s[48:49]
	v_cndmask_b32_dpp v76, v188, v190, vcc quad_perm:[2,3,0,1] row_mask:0xf bank_mask:0xf
	v_cndmask_b32_dpp v77, v189, v191, vcc quad_perm:[2,3,0,1] row_mask:0xf bank_mask:0xf
	s_mov_b64 vcc, s[50:51]
	v_lshl_add_u32 v192, v158, 9, v192
	v_cvt_pk_bf16_f32 v77, v76, v77
	v_cvt_pk_bf16_f32 v76, v74, v75
	v_add_u32_e32 v192, v192, v226
	v_mov_b32_e32 v193, v1
	v_lshl_add_u64 v[192:193], s[72:73], 0, v[192:193]
	global_store_dwordx2 v[192:193], v[76:77], off

; __device__ __forceinline__ bf16_t f2bf(float x) { return (bf16_t)(cvt_pk_bf16(x, 0.f) & 0xffffu); }
; __device__ __forceinline__ void st_bf4(bf16_t* p, f32x4 v) { u32x2 w; w.x = cvt_pk_bf16(v[0], v[1]); w.y = cvt_pk_bf16(v[2], v[3]); *(u32x2*)p = w; }
;     __device__ __forceinline__ void operator()(const Acc& acc, const Unit& u, int wr, int wc, int fr, int fq) const {
;     ...
;                     for (int n = 0; n < 2; ++n) { const int col = col0 + bj * 128 + n * 16; const f32x4 v = acc[ai][bj][m][n] * rs;
;                         if (col < 512) st_bf4(Kb + (size_t)row * 512 + col, v);
;                         else {
; #pragma unroll
;                             for (int j = 0; j < 4; ++j) Vt[((size_t)(row >> 8) * 512 + (col - 512 + j)) * 256 + (row & 255)] = f2bf(v[j]); } } }
.LBB0_606:
	s_or_b64 exec, exec, s[26:27]
	v_mov_b32_e32 v74, v82
	v_mov_b32_e32 v75, v82
	v_pk_mul_f32 v[72:73], v[72:73], v[74:75]
	v_pk_mul_f32 v[70:71], v[70:71], v[82:83]
	s_and_saveexec_b64 s[26:27], s[6:7]
	s_xor_b64 s[26:27], exec, s[26:27]
	s_cbranch_execz .LBB0_608
	v_and_b32_e32 v192, -8, v0
	s_add_u32 s72, s18, s24
	s_addc_u32 s73, s19, s25
	s_mov_b64 s[50:51], vcc
	s_mov_b64 vcc, s[40:41]
	v_cndmask_b32_dpp v188, v71, v70, vcc quad_perm:[1,0,3,2] row_mask:0xf bank_mask:0xf
	v_cndmask_b32_dpp v190, v73, v72, vcc quad_perm:[1,0,3,2] row_mask:0xf bank_mask:0xf
	s_mov_b64 vcc, s[42:43]
	v_cndmask_b32_dpp v189, v70, v71, vcc quad_perm:[1,0,3,2] row_mask:0xf bank_mask:0xf
	v_cndmask_b32_dpp v191, v72, v73, vcc quad_perm:[1,0,3,2] row_mask:0xf bank_mask:0xf
	s_mov_b64 vcc, s[46:47]
	v_cndmask_b32_dpp v70, v190, v188, vcc quad_perm:[2,3,0,1] row_mask:0xf bank_mask:0xf
	v_cndmask_b32_dpp v71, v191, v189, vcc quad_perm:[2,3,0,1] row_mask:0xf bank_mask:0xf
	s_mov_b64 vcc, s[48:49]
	v_cndmask_b32_dpp v72, v188, v190, vcc quad_perm:[2,3,0,1] row_mask:0xf bank_mask:0xf
	v_cndmask_b32_dpp v73, v189, v191, vcc quad_perm:[2,3,0,1] row_mask:0xf bank_mask:0xf
	s_mov_b64 vcc, s[50:51]
	v_lshl_add_u32 v192, v162, 9, v192
	v_cvt_pk_bf16_f32 v73, v72, v73
	v_cvt_pk_bf16_f32 v72, v70, v71
	v_add_u32_e32 v192, v192, v226
	v_mov_b32_e32 v193, v1
	v_lshl_add_u64 v[192:193], s[72:73], 0, v[192:193]
	global_store_dwordx2 v[192:193], v[72:73], off

; __device__ __forceinline__ bf16_t f2bf(float x) { return (bf16_t)(cvt_pk_bf16(x, 0.f) & 0xffffu); }
; __device__ __forceinline__ void st_bf4(bf16_t* p, f32x4 v) { u32x2 w; w.x = cvt_pk_bf16(v[0], v[1]); w.y = cvt_pk_bf16(v[2], v[3]); *(u32x2*)p = w; }
;     __device__ __forceinline__ void operator()(const Acc& acc, const Unit& u, int wr, int wc, int fr, int fq) const {
;     ...
;                     for (int n = 0; n < 2; ++n) { const int col = col0 + bj * 128 + n * 16; const f32x4 v = acc[ai][bj][m][n] * rs;
;                         if (col < 512) st_bf4(Kb + (size_t)row * 512 + col, v);
;                         else {
; #pragma unroll
;                             for (int j = 0; j < 4; ++j) Vt[((size_t)(row >> 8) * 512 + (col - 512 + j)) * 256 + (row & 255)] = f2bf(v[j]); } } }
.LBB0_610:
	s_or_b64 exec, exec, s[26:27]
	v_mov_b32_e32 v70, v82
	v_mov_b32_e32 v71, v82
	v_pk_mul_f32 v[68:69], v[68:69], v[70:71]
	v_pk_mul_f32 v[66:67], v[66:67], v[82:83]
	s_and_saveexec_b64 s[26:27], s[8:9]
	s_xor_b64 s[26:27], exec, s[26:27]
	s_cbranch_execz .LBB0_612
	v_and_b32_e32 v192, -8, v0
	s_add_u32 s24, s18, s24
	s_addc_u32 s25, s19, s25
	s_mov_b64 s[50:51], vcc
	s_mov_b64 vcc, s[40:41]
	v_cndmask_b32_dpp v188, v67, v66, vcc quad_perm:[1,0,3,2] row_mask:0xf bank_mask:0xf
	v_cndmask_b32_dpp v190, v69, v68, vcc quad_perm:[1,0,3,2] row_mask:0xf bank_mask:0xf
	s_mov_b64 vcc, s[42:43]
	v_cndmask_b32_dpp v189, v66, v67, vcc quad_perm:[1,0,3,2] row_mask:0xf bank_mask:0xf
	v_cndmask_b32_dpp v191, v68, v69, vcc quad_perm:[1,0,3,2] row_mask:0xf bank_mask:0xf
	s_mov_b64 vcc, s[46:47]
	v_cndmask_b32_dpp v66, v190, v188, vcc quad_perm:[2,3,0,1] row_mask:0xf bank_mask:0xf
	v_cndmask_b32_dpp v67, v191, v189, vcc quad_perm:[2,3,0,1] row_mask:0xf bank_mask:0xf
	s_mov_b64 vcc, s[48:49]
	v_cndmask_b32_dpp v68, v188, v190, vcc quad_perm:[2,3,0,1] row_mask:0xf bank_mask:0xf
	v_cndmask_b32_dpp v69, v189, v191, vcc quad_perm:[2,3,0,1] row_mask:0xf bank_mask:0xf
	s_mov_b64 vcc, s[50:51]
	v_lshl_add_u32 v192, v166, 9, v192
	v_cvt_pk_bf16_f32 v69, v68, v69
	v_cvt_pk_bf16_f32 v68, v66, v67
	v_add_u32_e32 v192, v192, v226
	v_mov_b32_e32 v193, v1
	v_lshl_add_u64 v[192:193], s[24:25], 0, v[192:193]
	global_store_dwordx2 v[192:193], v[68:69], off

; __device__ __forceinline__ bf16_t f2bf(float x) { return (bf16_t)(cvt_pk_bf16(x, 0.f) & 0xffffu); }
;     __device__ __forceinline__ void operator()(const Acc& acc, const Unit& u, int wr, int wc, int fr, int fq) const {
;     ...
;             for (int m = 0; m < 4; ++m) { const int row = row0 + ai * 128 + m * 16; const float rs = rstd[row];
;     ...
;                             for (int j = 0; j < 4; ++j) Vt[((size_t)(row >> 8) * 512 + (col - 512 + j)) * 256 + (row & 255)] = f2bf(v[j]); } } }
.LBB0_614:
	s_or_b64 exec, exec, s[24:25]
	v_mov_b32_e32 v68, v197
	v_add_u32_e32 v70, 0x80, v148
	v_ashrrev_i32_e32 v66, 8, v70
	v_ashrrev_i32_e32 v67, 31, v66
	v_and_b32_e32 v0, 0xcf, v70
	v_lshlrev_b64 v[66:67], 18, v[66:67]
	v_lshl_add_u64 v[66:67], s[18:19], 0, v[66:67]
	v_lshlrev_b32_e32 v0, 1, v0

; __device__ __forceinline__ bf16_t f2bf(float x) { return (bf16_t)(cvt_pk_bf16(x, 0.f) & 0xffffu); }
; __device__ __forceinline__ void st_bf4(bf16_t* p, f32x4 v) { u32x2 w; w.x = cvt_pk_bf16(v[0], v[1]); w.y = cvt_pk_bf16(v[2], v[3]); *(u32x2*)p = w; }
;     __device__ __forceinline__ void operator()(const Acc& acc, const Unit& u, int wr, int wc, int fr, int fq) const {
;     ...
;                     for (int n = 0; n < 2; ++n) { const int col = col0 + bj * 128 + n * 16; const f32x4 v = acc[ai][bj][m][n] * rs;
;                         if (col < 512) st_bf4(Kb + (size_t)row * 512 + col, v);
;                         else {
; #pragma unroll
;                             for (int j = 0; j < 4; ++j) Vt[((size_t)(row >> 8) * 512 + (col - 512 + j)) * 256 + (row & 255)] = f2bf(v[j]); } } }
	v_pk_mul_f32 v[64:65], v[64:65], v[68:69] op_sel_hi:[1,0]
	v_pk_mul_f32 v[72:73], v[62:63], v[68:69] op_sel_hi:[1,0]
	s_and_saveexec_b64 s[24:25], vcc
	s_xor_b64 s[24:25], exec, s[24:25]
	s_cbranch_execz .LBB0_616
	v_and_b32_e32 v192, -8, v0
	s_mov_b64 s[50:51], vcc
	s_mov_b64 vcc, s[40:41]
	v_cndmask_b32_dpp v188, v73, v72, vcc quad_perm:[1,0,3,2] row_mask:0xf bank_mask:0xf
	v_cndmask_b32_dpp v190, v65, v64, vcc quad_perm:[1,0,3,2] row_mask:0xf bank_mask:0xf
	s_mov_b64 vcc, s[42:43]
	v_cndmask_b32_dpp v189, v72, v73, vcc quad_perm:[1,0,3,2] row_mask:0xf bank_mask:0xf
	v_cndmask_b32_dpp v191, v64, v65, vcc quad_perm:[1,0,3,2] row_mask:0xf bank_mask:0xf
	s_mov_b64 vcc, s[46:47]
	v_cndmask_b32_dpp v72, v190, v188, vcc quad_perm:[2,3,0,1] row_mask:0xf bank_mask:0xf
	v_cndmask_b32_dpp v73, v191, v189, vcc quad_perm:[2,3,0,1] row_mask:0xf bank_mask:0xf
	s_mov_b64 vcc, s[48:49]
	v_cndmask_b32_dpp v64, v188, v190, vcc quad_perm:[2,3,0,1] row_mask:0xf bank_mask:0xf
	v_cndmask_b32_dpp v65, v189, v191, vcc quad_perm:[2,3,0,1] row_mask:0xf bank_mask:0xf
	s_mov_b64 vcc, s[50:51]
	v_lshl_add_u32 v192, v154, 9, v192
	v_cvt_pk_bf16_f32 v65, v64, v65
	v_cvt_pk_bf16_f32 v64, v72, v73
	v_add_u32_e32 v192, v192, v226
	v_mov_b32_e32 v193, v1
	v_lshl_add_u64 v[192:193], v[66:67], 0, v[192:193]
	global_store_dwordx2 v[192:193], v[64:65], off

; __device__ __forceinline__ bf16_t f2bf(float x) { return (bf16_t)(cvt_pk_bf16(x, 0.f) & 0xffffu); }
; __device__ __forceinline__ void st_bf4(bf16_t* p, f32x4 v) { u32x2 w; w.x = cvt_pk_bf16(v[0], v[1]); w.y = cvt_pk_bf16(v[2], v[3]); *(u32x2*)p = w; }
;     __device__ __forceinline__ void operator()(const Acc& acc, const Unit& u, int wr, int wc, int fr, int fq) const {
;     ...
;                     for (int n = 0; n < 2; ++n) { const int col = col0 + bj * 128 + n * 16; const f32x4 v = acc[ai][bj][m][n] * rs;
;                         if (col < 512) st_bf4(Kb + (size_t)row * 512 + col, v);
;                         else {
; #pragma unroll
;                             for (int j = 0; j < 4; ++j) Vt[((size_t)(row >> 8) * 512 + (col - 512 + j)) * 256 + (row & 255)] = f2bf(v[j]); } } }
.LBB0_618:
	s_or_b64 exec, exec, s[24:25]
	v_mov_b32_e32 v69, v68
	v_mov_b32_e32 v64, v68
	v_mov_b32_e32 v65, v68
	v_pk_mul_f32 v[60:61], v[60:61], v[64:65]
	v_pk_mul_f32 v[58:59], v[58:59], v[68:69]
	s_and_saveexec_b64 s[24:25], s[4:5]
	s_xor_b64 s[24:25], exec, s[24:25]
	s_cbranch_execz .LBB0_620
	v_and_b32_e32 v192, -8, v0
	s_mov_b64 s[50:51], vcc
	s_mov_b64 vcc, s[40:41]
	v_cndmask_b32_dpp v188, v59, v58, vcc quad_perm:[1,0,3,2] row_mask:0xf bank_mask:0xf
	v_cndmask_b32_dpp v190, v61, v60, vcc quad_perm:[1,0,3,2] row_mask:0xf bank_mask:0xf
	s_mov_b64 vcc, s[42:43]
	v_cndmask_b32_dpp v189, v58, v59, vcc quad_perm:[1,0,3,2] row_mask:0xf bank_mask:0xf
	v_cndmask_b32_dpp v191, v60, v61, vcc quad_perm:[1,0,3,2] row_mask:0xf bank_mask:0xf
	s_mov_b64 vcc, s[46:47]
	v_cndmask_b32_dpp v58, v190, v188, vcc quad_perm:[2,3,0,1] row_mask:0xf bank_mask:0xf
	v_cndmask_b32_dpp v59, v191, v189, vcc quad_perm:[2,3,0,1] row_mask:0xf bank_mask:0xf
	s_mov_b64 vcc, s[48:49]
	v_cndmask_b32_dpp v60, v188, v190, vcc quad_perm:[2,3,0,1] row_mask:0xf bank_mask:0xf
	v_cndmask_b32_dpp v61, v189, v191, vcc quad_perm:[2,3,0,1] row_mask:0xf bank_mask:0xf
	s_mov_b64 vcc, s[50:51]
	v_lshl_add_u32 v192, v158, 9, v192
	v_cvt_pk_bf16_f32 v61, v60, v61
	v_cvt_pk_bf16_f32 v60, v58, v59
	v_add_u32_e32 v192, v192, v226
	v_mov_b32_e32 v193, v1
	v_lshl_add_u64 v[192:193], v[66:67], 0, v[192:193]
	global_store_dwordx2 v[192:193], v[60:61], off

; __device__ __forceinline__ bf16_t f2bf(float x) { return (bf16_t)(cvt_pk_bf16(x, 0.f) & 0xffffu); }
; __device__ __forceinline__ void st_bf4(bf16_t* p, f32x4 v) { u32x2 w; w.x = cvt_pk_bf16(v[0], v[1]); w.y = cvt_pk_bf16(v[2], v[3]); *(u32x2*)p = w; }
;     __device__ __forceinline__ void operator()(const Acc& acc, const Unit& u, int wr, int wc, int fr, int fq) const {
;     ...
;                     for (int n = 0; n < 2; ++n) { const int col = col0 + bj * 128 + n * 16; const f32x4 v = acc[ai][bj][m][n] * rs;
;                         if (col < 512) st_bf4(Kb + (size_t)row * 512 + col, v);
;                         else {
; #pragma unroll
;                             for (int j = 0; j < 4; ++j) Vt[((size_t)(row >> 8) * 512 + (col - 512 + j)) * 256 + (row & 255)] = f2bf(v[j]); } } }
.LBB0_622:
	s_or_b64 exec, exec, s[24:25]
	v_mov_b32_e32 v58, v68
	v_mov_b32_e32 v59, v68
	v_pk_mul_f32 v[56:57], v[56:57], v[58:59]
	v_pk_mul_f32 v[54:55], v[54:55], v[68:69]
	s_and_saveexec_b64 s[24:25], s[6:7]
	s_xor_b64 s[24:25], exec, s[24:25]
	s_cbranch_execz .LBB0_624
	v_and_b32_e32 v192, -8, v0
	s_mov_b64 s[50:51], vcc
	s_mov_b64 vcc, s[40:41]
	v_cndmask_b32_dpp v188, v55, v54, vcc quad_perm:[1,0,3,2] row_mask:0xf bank_mask:0xf
	v_cndmask_b32_dpp v190, v57, v56, vcc quad_perm:[1,0,3,2] row_mask:0xf bank_mask:0xf
	s_mov_b64 vcc, s[42:43]
	v_cndmask_b32_dpp v189, v54, v55, vcc quad_perm:[1,0,3,2] row_mask:0xf bank_mask:0xf
	v_cndmask_b32_dpp v191, v56, v57, vcc quad_perm:[1,0,3,2] row_mask:0xf bank_mask:0xf
	s_mov_b64 vcc, s[46:47]
	v_cndmask_b32_dpp v54, v190, v188, vcc quad_perm:[2,3,0,1] row_mask:0xf bank_mask:0xf
	v_cndmask_b32_dpp v55, v191, v189, vcc quad_perm:[2,3,0,1] row_mask:0xf bank_mask:0xf
	s_mov_b64 vcc, s[48:49]
	v_cndmask_b32_dpp v56, v188, v190, vcc quad_perm:[2,3,0,1] row_mask:0xf bank_mask:0xf
	v_cndmask_b32_dpp v57, v189, v191, vcc quad_perm:[2,3,0,1] row_mask:0xf bank_mask:0xf
	s_mov_b64 vcc, s[50:51]
	v_lshl_add_u32 v192, v162, 9, v192
	v_cvt_pk_bf16_f32 v57, v56, v57
	v_cvt_pk_bf16_f32 v56, v54, v55
	v_add_u32_e32 v192, v192, v226
	v_mov_b32_e32 v193, v1
	v_lshl_add_u64 v[192:193], v[66:67], 0, v[192:193]
	global_store_dwordx2 v[192:193], v[56:57], off

; __device__ __forceinline__ bf16_t f2bf(float x) { return (bf16_t)(cvt_pk_bf16(x, 0.f) & 0xffffu); }
; __device__ __forceinline__ void st_bf4(bf16_t* p, f32x4 v) { u32x2 w; w.x = cvt_pk_bf16(v[0], v[1]); w.y = cvt_pk_bf16(v[2], v[3]); *(u32x2*)p = w; }
;     __device__ __forceinline__ void operator()(const Acc& acc, const Unit& u, int wr, int wc, int fr, int fq) const {
;     ...
;                     for (int n = 0; n < 2; ++n) { const int col = col0 + bj * 128 + n * 16; const f32x4 v = acc[ai][bj][m][n] * rs;
;                         if (col < 512) st_bf4(Kb + (size_t)row * 512 + col, v);
;                         else {
; #pragma unroll
;                             for (int j = 0; j < 4; ++j) Vt[((size_t)(row >> 8) * 512 + (col - 512 + j)) * 256 + (row & 255)] = f2bf(v[j]); } } }
.LBB0_626:
	s_or_b64 exec, exec, s[24:25]
	v_mov_b32_e32 v54, v68
	v_mov_b32_e32 v55, v68
	v_pk_mul_f32 v[52:53], v[52:53], v[54:55]
	v_pk_mul_f32 v[50:51], v[50:51], v[68:69]
	s_and_saveexec_b64 s[24:25], s[8:9]
	s_xor_b64 s[24:25], exec, s[24:25]
	s_cbranch_execz .LBB0_628
	v_and_b32_e32 v192, -8, v0
	s_mov_b64 s[50:51], vcc
	s_mov_b64 vcc, s[40:41]
	v_cndmask_b32_dpp v188, v51, v50, vcc quad_perm:[1,0,3,2] row_mask:0xf bank_mask:0xf
	v_cndmask_b32_dpp v190, v53, v52, vcc quad_perm:[1,0,3,2] row_mask:0xf bank_mask:0xf
	s_mov_b64 vcc, s[42:43]
	v_cndmask_b32_dpp v189, v50, v51, vcc quad_perm:[1,0,3,2] row_mask:0xf bank_mask:0xf
	v_cndmask_b32_dpp v191, v52, v53, vcc quad_perm:[1,0,3,2] row_mask:0xf bank_mask:0xf
	s_mov_b64 vcc, s[46:47]
	v_cndmask_b32_dpp v50, v190, v188, vcc quad_perm:[2,3,0,1] row_mask:0xf bank_mask:0xf
	v_cndmask_b32_dpp v51, v191, v189, vcc quad_perm:[2,3,0,1] row_mask:0xf bank_mask:0xf
	s_mov_b64 vcc, s[48:49]
	v_cndmask_b32_dpp v52, v188, v190, vcc quad_perm:[2,3,0,1] row_mask:0xf bank_mask:0xf
	v_cndmask_b32_dpp v53, v189, v191, vcc quad_perm:[2,3,0,1] row_mask:0xf bank_mask:0xf
	s_mov_b64 vcc, s[50:51]
	v_lshl_add_u32 v192, v166, 9, v192
	v_cvt_pk_bf16_f32 v53, v52, v53
	v_cvt_pk_bf16_f32 v52, v50, v51
	v_add_u32_e32 v192, v192, v226
	v_mov_b32_e32 v193, v1
	v_lshl_add_u64 v[192:193], v[66:67], 0, v[192:193]
	global_store_dwordx2 v[192:193], v[52:53], off

;     __device__ __forceinline__ void operator()(const Acc& acc, const Unit& u, int wr, int wc, int fr, int fq) const {
;     ...
;             for (int m = 0; m < 4; ++m) { const int row = row0 + ai * 128 + m * 16; const float rs = rstd[row];
.LBB0_630:
	s_or_b64 exec, exec, s[24:25]
	v_mov_b32_e32 v50, v198
	v_add_u32_e32 v52, 0x90, v148
	v_and_b32_e32 v0, 0xdf, v52
	v_lshlrev_b32_e32 v0, 1, v0

; __device__ __forceinline__ bf16_t f2bf(float x) { return (bf16_t)(cvt_pk_bf16(x, 0.f) & 0xffffu); }
; __device__ __forceinline__ void st_bf4(bf16_t* p, f32x4 v) { u32x2 w; w.x = cvt_pk_bf16(v[0], v[1]); w.y = cvt_pk_bf16(v[2], v[3]); *(u32x2*)p = w; }
;     __device__ __forceinline__ void operator()(const Acc& acc, const Unit& u, int wr, int wc, int fr, int fq) const {
;     ...
;             for (int m = 0; m < 4; ++m) { const int row = row0 + ai * 128 + m * 16; const float rs = rstd[row];
; #pragma unroll
;                 for (int bj = 0; bj < 2; ++bj)
; #pragma unroll
;                     for (int n = 0; n < 2; ++n) { const int col = col0 + bj * 128 + n * 16; const f32x4 v = acc[ai][bj][m][n] * rs;
;                         if (col < 512) st_bf4(Kb + (size_t)row * 512 + col, v);
;                         else {
; #pragma unroll
;                             for (int j = 0; j < 4; ++j) Vt[((size_t)(row >> 8) * 512 + (col - 512 + j)) * 256 + (row & 255)] = f2bf(v[j]); } } }
	v_pk_mul_f32 v[48:49], v[48:49], v[50:51] op_sel_hi:[1,0]
	v_pk_mul_f32 v[54:55], v[46:47], v[50:51] op_sel_hi:[1,0]
	s_and_saveexec_b64 s[24:25], vcc
	s_xor_b64 s[24:25], exec, s[24:25]
	s_cbranch_execz .LBB0_632
	v_and_b32_e32 v192, -8, v0
	s_mov_b64 s[50:51], vcc
	s_mov_b64 vcc, s[40:41]
	v_cndmask_b32_dpp v188, v55, v54, vcc quad_perm:[1,0,3,2] row_mask:0xf bank_mask:0xf
	v_cndmask_b32_dpp v190, v49, v48, vcc quad_perm:[1,0,3,2] row_mask:0xf bank_mask:0xf
	s_mov_b64 vcc, s[42:43]
	v_cndmask_b32_dpp v189, v54, v55, vcc quad_perm:[1,0,3,2] row_mask:0xf bank_mask:0xf
	v_cndmask_b32_dpp v191, v48, v49, vcc quad_perm:[1,0,3,2] row_mask:0xf bank_mask:0xf
	s_mov_b64 vcc, s[46:47]
	v_cndmask_b32_dpp v54, v190, v188, vcc quad_perm:[2,3,0,1] row_mask:0xf bank_mask:0xf
	v_cndmask_b32_dpp v55, v191, v189, vcc quad_perm:[2,3,0,1] row_mask:0xf bank_mask:0xf
	s_mov_b64 vcc, s[48:49]
	v_cndmask_b32_dpp v48, v188, v190, vcc quad_perm:[2,3,0,1] row_mask:0xf bank_mask:0xf
	v_cndmask_b32_dpp v49, v189, v191, vcc quad_perm:[2,3,0,1] row_mask:0xf bank_mask:0xf
	s_mov_b64 vcc, s[50:51]
	v_lshl_add_u32 v192, v154, 9, v192
	v_cvt_pk_bf16_f32 v49, v48, v49
	v_cvt_pk_bf16_f32 v48, v54, v55
	v_add_u32_e32 v192, v192, v226
	v_mov_b32_e32 v193, v1
	v_lshl_add_u64 v[192:193], v[66:67], 0, v[192:193]
	global_store_dwordx2 v[192:193], v[48:49], off

; __device__ __forceinline__ bf16_t f2bf(float x) { return (bf16_t)(cvt_pk_bf16(x, 0.f) & 0xffffu); }
; __device__ __forceinline__ void st_bf4(bf16_t* p, f32x4 v) { u32x2 w; w.x = cvt_pk_bf16(v[0], v[1]); w.y = cvt_pk_bf16(v[2], v[3]); *(u32x2*)p = w; }
;     __device__ __forceinline__ void operator()(const Acc& acc, const Unit& u, int wr, int wc, int fr, int fq) const {
;     ...
;             for (int m = 0; m < 4; ++m) { const int row = row0 + ai * 128 + m * 16; const float rs = rstd[row];
; #pragma unroll
;                 for (int bj = 0; bj < 2; ++bj)
; #pragma unroll
;                     for (int n = 0; n < 2; ++n) { const int col = col0 + bj * 128 + n * 16; const f32x4 v = acc[ai][bj][m][n] * rs;
;                         if (col < 512) st_bf4(Kb + (size_t)row * 512 + col, v);
;                         else {
; #pragma unroll
;                             for (int j = 0; j < 4; ++j) Vt[((size_t)(row >> 8) * 512 + (col - 512 + j)) * 256 + (row & 255)] = f2bf(v[j]); } } }
.LBB0_634:
	s_or_b64 exec, exec, s[24:25]
	v_mov_b32_e32 v51, v50
	v_mov_b32_e32 v48, v50
	v_mov_b32_e32 v49, v50
	v_pk_mul_f32 v[44:45], v[44:45], v[48:49]
	v_pk_mul_f32 v[42:43], v[42:43], v[50:51]
	s_and_saveexec_b64 s[24:25], s[4:5]
	s_xor_b64 s[24:25], exec, s[24:25]
	s_cbranch_execz .LBB0_636
	v_and_b32_e32 v192, -8, v0
	s_mov_b64 s[50:51], vcc
	s_mov_b64 vcc, s[40:41]
	v_cndmask_b32_dpp v188, v43, v42, vcc quad_perm:[1,0,3,2] row_mask:0xf bank_mask:0xf
	v_cndmask_b32_dpp v190, v45, v44, vcc quad_perm:[1,0,3,2] row_mask:0xf bank_mask:0xf
	s_mov_b64 vcc, s[42:43]
	v_cndmask_b32_dpp v189, v42, v43, vcc quad_perm:[1,0,3,2] row_mask:0xf bank_mask:0xf
	v_cndmask_b32_dpp v191, v44, v45, vcc quad_perm:[1,0,3,2] row_mask:0xf bank_mask:0xf
	s_mov_b64 vcc, s[46:47]
	v_cndmask_b32_dpp v42, v190, v188, vcc quad_perm:[2,3,0,1] row_mask:0xf bank_mask:0xf
	v_cndmask_b32_dpp v43, v191, v189, vcc quad_perm:[2,3,0,1] row_mask:0xf bank_mask:0xf
	s_mov_b64 vcc, s[48:49]
	v_cndmask_b32_dpp v44, v188, v190, vcc quad_perm:[2,3,0,1] row_mask:0xf bank_mask:0xf
	v_cndmask_b32_dpp v45, v189, v191, vcc quad_perm:[2,3,0,1] row_mask:0xf bank_mask:0xf
	s_mov_b64 vcc, s[50:51]
	v_lshl_add_u32 v192, v158, 9, v192
	v_cvt_pk_bf16_f32 v45, v44, v45
	v_cvt_pk_bf16_f32 v44, v42, v43
	v_add_u32_e32 v192, v192, v226
	v_mov_b32_e32 v193, v1
	v_lshl_add_u64 v[192:193], v[66:67], 0, v[192:193]
	global_store_dwordx2 v[192:193], v[44:45], off

; __device__ __forceinline__ bf16_t f2bf(float x) { return (bf16_t)(cvt_pk_bf16(x, 0.f) & 0xffffu); }
; __device__ __forceinline__ void st_bf4(bf16_t* p, f32x4 v) { u32x2 w; w.x = cvt_pk_bf16(v[0], v[1]); w.y = cvt_pk_bf16(v[2], v[3]); *(u32x2*)p = w; }
;     __device__ __forceinline__ void operator()(const Acc& acc, const Unit& u, int wr, int wc, int fr, int fq) const {
;     ...
;             for (int m = 0; m < 4; ++m) { const int row = row0 + ai * 128 + m * 16; const float rs = rstd[row];
; #pragma unroll
;                 for (int bj = 0; bj < 2; ++bj)
; #pragma unroll
;                     for (int n = 0; n < 2; ++n) { const int col = col0 + bj * 128 + n * 16; const f32x4 v = acc[ai][bj][m][n] * rs;
;                         if (col < 512) st_bf4(Kb + (size_t)row * 512 + col, v);
;                         else {
; #pragma unroll
;                             for (int j = 0; j < 4; ++j) Vt[((size_t)(row >> 8) * 512 + (col - 512 + j)) * 256 + (row & 255)] = f2bf(v[j]); } } }
.LBB0_638:
	s_or_b64 exec, exec, s[24:25]
	v_mov_b32_e32 v42, v50
	v_mov_b32_e32 v43, v50
	v_pk_mul_f32 v[40:41], v[40:41], v[42:43]
	v_pk_mul_f32 v[38:39], v[38:39], v[50:51]
	s_and_saveexec_b64 s[24:25], s[6:7]
	s_xor_b64 s[24:25], exec, s[24:25]
	s_cbranch_execz .LBB0_640
	v_and_b32_e32 v192, -8, v0
	s_mov_b64 s[50:51], vcc
	s_mov_b64 vcc, s[40:41]
	v_cndmask_b32_dpp v188, v39, v38, vcc quad_perm:[1,0,3,2] row_mask:0xf bank_mask:0xf
	v_cndmask_b32_dpp v190, v41, v40, vcc quad_perm:[1,0,3,2] row_mask:0xf bank_mask:0xf
	s_mov_b64 vcc, s[42:43]
	v_cndmask_b32_dpp v189, v38, v39, vcc quad_perm:[1,0,3,2] row_mask:0xf bank_mask:0xf
	v_cndmask_b32_dpp v191, v40, v41, vcc quad_perm:[1,0,3,2] row_mask:0xf bank_mask:0xf
	s_mov_b64 vcc, s[46:47]
	v_cndmask_b32_dpp v38, v190, v188, vcc quad_perm:[2,3,0,1] row_mask:0xf bank_mask:0xf
	v_cndmask_b32_dpp v39, v191, v189, vcc quad_perm:[2,3,0,1] row_mask:0xf bank_mask:0xf
	s_mov_b64 vcc, s[48:49]
	v_cndmask_b32_dpp v40, v188, v190, vcc quad_perm:[2,3,0,1] row_mask:0xf bank_mask:0xf
	v_cndmask_b32_dpp v41, v189, v191, vcc quad_perm:[2,3,0,1] row_mask:0xf bank_mask:0xf
	s_mov_b64 vcc, s[50:51]
	v_lshl_add_u32 v192, v162, 9, v192
	v_cvt_pk_bf16_f32 v41, v40, v41
	v_cvt_pk_bf16_f32 v40, v38, v39
	v_add_u32_e32 v192, v192, v226
	v_mov_b32_e32 v193, v1
	v_lshl_add_u64 v[192:193], v[66:67], 0, v[192:193]
	global_store_dwordx2 v[192:193], v[40:41], off

; __device__ __forceinline__ bf16_t f2bf(float x) { return (bf16_t)(cvt_pk_bf16(x, 0.f) & 0xffffu); }
; __device__ __forceinline__ void st_bf4(bf16_t* p, f32x4 v) { u32x2 w; w.x = cvt_pk_bf16(v[0], v[1]); w.y = cvt_pk_bf16(v[2], v[3]); *(u32x2*)p = w; }
;     __device__ __forceinline__ void operator()(const Acc& acc, const Unit& u, int wr, int wc, int fr, int fq) const {
;     ...
;             for (int m = 0; m < 4; ++m) { const int row = row0 + ai * 128 + m * 16; const float rs = rstd[row];
; #pragma unroll
;                 for (int bj = 0; bj < 2; ++bj)
; #pragma unroll
;                     for (int n = 0; n < 2; ++n) { const int col = col0 + bj * 128 + n * 16; const f32x4 v = acc[ai][bj][m][n] * rs;
;                         if (col < 512) st_bf4(Kb + (size_t)row * 512 + col, v);
;                         else {
; #pragma unroll
;                             for (int j = 0; j < 4; ++j) Vt[((size_t)(row >> 8) * 512 + (col - 512 + j)) * 256 + (row & 255)] = f2bf(v[j]); } } }
.LBB0_642:
	s_or_b64 exec, exec, s[24:25]
	v_mov_b32_e32 v38, v50
	v_mov_b32_e32 v39, v50
	v_pk_mul_f32 v[36:37], v[36:37], v[38:39]
	v_pk_mul_f32 v[34:35], v[34:35], v[50:51]
	s_and_saveexec_b64 s[24:25], s[8:9]
	s_xor_b64 s[24:25], exec, s[24:25]
	s_cbranch_execz .LBB0_644
	v_and_b32_e32 v192, -8, v0
	s_mov_b64 s[50:51], vcc
	s_mov_b64 vcc, s[40:41]
	v_cndmask_b32_dpp v188, v35, v34, vcc quad_perm:[1,0,3,2] row_mask:0xf bank_mask:0xf
	v_cndmask_b32_dpp v190, v37, v36, vcc quad_perm:[1,0,3,2] row_mask:0xf bank_mask:0xf
	s_mov_b64 vcc, s[42:43]
	v_cndmask_b32_dpp v189, v34, v35, vcc quad_perm:[1,0,3,2] row_mask:0xf bank_mask:0xf
	v_cndmask_b32_dpp v191, v36, v37, vcc quad_perm:[1,0,3,2] row_mask:0xf bank_mask:0xf
	s_mov_b64 vcc, s[46:47]
	v_cndmask_b32_dpp v34, v190, v188, vcc quad_perm:[2,3,0,1] row_mask:0xf bank_mask:0xf
	v_cndmask_b32_dpp v35, v191, v189, vcc quad_perm:[2,3,0,1] row_mask:0xf bank_mask:0xf
	s_mov_b64 vcc, s[48:49]
	v_cndmask_b32_dpp v36, v188, v190, vcc quad_perm:[2,3,0,1] row_mask:0xf bank_mask:0xf
	v_cndmask_b32_dpp v37, v189, v191, vcc quad_perm:[2,3,0,1] row_mask:0xf bank_mask:0xf
	s_mov_b64 vcc, s[50:51]
	v_lshl_add_u32 v192, v166, 9, v192
	v_cvt_pk_bf16_f32 v37, v36, v37
	v_cvt_pk_bf16_f32 v36, v34, v35
	v_add_u32_e32 v192, v192, v226
	v_mov_b32_e32 v193, v1
	v_lshl_add_u64 v[192:193], v[66:67], 0, v[192:193]
	global_store_dwordx2 v[192:193], v[36:37], off

;     __device__ __forceinline__ void operator()(const Acc& acc, const Unit& u, int wr, int wc, int fr, int fq) const {
;     ...
;             for (int m = 0; m < 4; ++m) { const int row = row0 + ai * 128 + m * 16; const float rs = rstd[row];
; #pragma unroll
;                 for (int bj = 0; bj < 2; ++bj)
; #pragma unroll
;                     for (int n = 0; n < 2; ++n) { const int col = col0 + bj * 128 + n * 16; const f32x4 v = acc[ai][bj][m][n] * rs;
.LBB0_646:
	s_or_b64 exec, exec, s[24:25]
	v_mov_b32_e32 v34, v199
	v_add_u32_e32 v36, 0xa0, v148
	v_and_b32_e32 v0, 0xef, v36
	v_lshlrev_b32_e32 v0, 1, v0

; __device__ __forceinline__ bf16_t f2bf(float x) { return (bf16_t)(cvt_pk_bf16(x, 0.f) & 0xffffu); }
; __device__ __forceinline__ void st_bf4(bf16_t* p, f32x4 v) { u32x2 w; w.x = cvt_pk_bf16(v[0], v[1]); w.y = cvt_pk_bf16(v[2], v[3]); *(u32x2*)p = w; }
;     __device__ __forceinline__ void operator()(const Acc& acc, const Unit& u, int wr, int wc, int fr, int fq) const {
;     ...
;             for (int m = 0; m < 4; ++m) { const int row = row0 + ai * 128 + m * 16; const float rs = rstd[row];
; #pragma unroll
;                 for (int bj = 0; bj < 2; ++bj)
; #pragma unroll
;                     for (int n = 0; n < 2; ++n) { const int col = col0 + bj * 128 + n * 16; const f32x4 v = acc[ai][bj][m][n] * rs;
;                         if (col < 512) st_bf4(Kb + (size_t)row * 512 + col, v);
;                         else {
; #pragma unroll
;                             for (int j = 0; j < 4; ++j) Vt[((size_t)(row >> 8) * 512 + (col - 512 + j)) * 256 + (row & 255)] = f2bf(v[j]); } } }
	v_pk_mul_f32 v[32:33], v[32:33], v[34:35] op_sel_hi:[1,0]
	v_pk_mul_f32 v[38:39], v[30:31], v[34:35] op_sel_hi:[1,0]
	s_and_saveexec_b64 s[24:25], vcc
	s_xor_b64 s[24:25], exec, s[24:25]
	s_cbranch_execz .LBB0_648
	v_and_b32_e32 v192, -8, v0
	s_mov_b64 s[50:51], vcc
	s_mov_b64 vcc, s[40:41]
	v_cndmask_b32_dpp v188, v39, v38, vcc quad_perm:[1,0,3,2] row_mask:0xf bank_mask:0xf
	v_cndmask_b32_dpp v190, v33, v32, vcc quad_perm:[1,0,3,2] row_mask:0xf bank_mask:0xf
	s_mov_b64 vcc, s[42:43]
	v_cndmask_b32_dpp v189, v38, v39, vcc quad_perm:[1,0,3,2] row_mask:0xf bank_mask:0xf
	v_cndmask_b32_dpp v191, v32, v33, vcc quad_perm:[1,0,3,2] row_mask:0xf bank_mask:0xf
	s_mov_b64 vcc, s[46:47]
	v_cndmask_b32_dpp v38, v190, v188, vcc quad_perm:[2,3,0,1] row_mask:0xf bank_mask:0xf
	v_cndmask_b32_dpp v39, v191, v189, vcc quad_perm:[2,3,0,1] row_mask:0xf bank_mask:0xf
	s_mov_b64 vcc, s[48:49]
	v_cndmask_b32_dpp v32, v188, v190, vcc quad_perm:[2,3,0,1] row_mask:0xf bank_mask:0xf
	v_cndmask_b32_dpp v33, v189, v191, vcc quad_perm:[2,3,0,1] row_mask:0xf bank_mask:0xf
	s_mov_b64 vcc, s[50:51]
	v_lshl_add_u32 v192, v154, 9, v192
	v_cvt_pk_bf16_f32 v33, v32, v33
	v_cvt_pk_bf16_f32 v32, v38, v39
	v_add_u32_e32 v192, v192, v226
	v_mov_b32_e32 v193, v1
	v_lshl_add_u64 v[192:193], v[66:67], 0, v[192:193]
	global_store_dwordx2 v[192:193], v[32:33], off

; __device__ __forceinline__ bf16_t f2bf(float x) { return (bf16_t)(cvt_pk_bf16(x, 0.f) & 0xffffu); }
; __device__ __forceinline__ void st_bf4(bf16_t* p, f32x4 v) { u32x2 w; w.x = cvt_pk_bf16(v[0], v[1]); w.y = cvt_pk_bf16(v[2], v[3]); *(u32x2*)p = w; }
;     __device__ __forceinline__ void operator()(const Acc& acc, const Unit& u, int wr, int wc, int fr, int fq) const {
;     ...
;             for (int m = 0; m < 4; ++m) { const int row = row0 + ai * 128 + m * 16; const float rs = rstd[row];
; #pragma unroll
;                 for (int bj = 0; bj < 2; ++bj)
; #pragma unroll
;                     for (int n = 0; n < 2; ++n) { const int col = col0 + bj * 128 + n * 16; const f32x4 v = acc[ai][bj][m][n] * rs;
;                         if (col < 512) st_bf4(Kb + (size_t)row * 512 + col, v);
;                         else {
; #pragma unroll
;                             for (int j = 0; j < 4; ++j) Vt[((size_t)(row >> 8) * 512 + (col - 512 + j)) * 256 + (row & 255)] = f2bf(v[j]); } } }
.LBB0_650:
	s_or_b64 exec, exec, s[24:25]
	v_mov_b32_e32 v35, v34
	v_mov_b32_e32 v32, v34
	v_mov_b32_e32 v33, v34
	v_pk_mul_f32 v[28:29], v[28:29], v[32:33]
	v_pk_mul_f32 v[26:27], v[26:27], v[34:35]
	s_and_saveexec_b64 s[24:25], s[4:5]
	s_xor_b64 s[24:25], exec, s[24:25]
	s_cbranch_execz .LBB0_652
	v_and_b32_e32 v192, -8, v0
	s_mov_b64 s[50:51], vcc
	s_mov_b64 vcc, s[40:41]
	v_cndmask_b32_dpp v188, v27, v26, vcc quad_perm:[1,0,3,2] row_mask:0xf bank_mask:0xf
	v_cndmask_b32_dpp v190, v29, v28, vcc quad_perm:[1,0,3,2] row_mask:0xf bank_mask:0xf
	s_mov_b64 vcc, s[42:43]
	v_cndmask_b32_dpp v189, v26, v27, vcc quad_perm:[1,0,3,2] row_mask:0xf bank_mask:0xf
	v_cndmask_b32_dpp v191, v28, v29, vcc quad_perm:[1,0,3,2] row_mask:0xf bank_mask:0xf
	s_mov_b64 vcc, s[46:47]
	v_cndmask_b32_dpp v26, v190, v188, vcc quad_perm:[2,3,0,1] row_mask:0xf bank_mask:0xf
	v_cndmask_b32_dpp v27, v191, v189, vcc quad_perm:[2,3,0,1] row_mask:0xf bank_mask:0xf
	s_mov_b64 vcc, s[48:49]
	v_cndmask_b32_dpp v28, v188, v190, vcc quad_perm:[2,3,0,1] row_mask:0xf bank_mask:0xf
	v_cndmask_b32_dpp v29, v189, v191, vcc quad_perm:[2,3,0,1] row_mask:0xf bank_mask:0xf
	s_mov_b64 vcc, s[50:51]
	v_lshl_add_u32 v192, v158, 9, v192
	v_cvt_pk_bf16_f32 v29, v28, v29
	v_cvt_pk_bf16_f32 v28, v26, v27
	v_add_u32_e32 v192, v192, v226
	v_mov_b32_e32 v193, v1
	v_lshl_add_u64 v[192:193], v[66:67], 0, v[192:193]
	global_store_dwordx2 v[192:193], v[28:29], off

; __device__ __forceinline__ bf16_t f2bf(float x) { return (bf16_t)(cvt_pk_bf16(x, 0.f) & 0xffffu); }
; __device__ __forceinline__ void st_bf4(bf16_t* p, f32x4 v) { u32x2 w; w.x = cvt_pk_bf16(v[0], v[1]); w.y = cvt_pk_bf16(v[2], v[3]); *(u32x2*)p = w; }
;     __device__ __forceinline__ void operator()(const Acc& acc, const Unit& u, int wr, int wc, int fr, int fq) const {
;     ...
;             for (int m = 0; m < 4; ++m) { const int row = row0 + ai * 128 + m * 16; const float rs = rstd[row];
; #pragma unroll
;                 for (int bj = 0; bj < 2; ++bj)
; #pragma unroll
;                     for (int n = 0; n < 2; ++n) { const int col = col0 + bj * 128 + n * 16; const f32x4 v = acc[ai][bj][m][n] * rs;
;                         if (col < 512) st_bf4(Kb + (size_t)row * 512 + col, v);
;                         else {
; #pragma unroll
;                             for (int j = 0; j < 4; ++j) Vt[((size_t)(row >> 8) * 512 + (col - 512 + j)) * 256 + (row & 255)] = f2bf(v[j]); } } }
.LBB0_654:
	s_or_b64 exec, exec, s[24:25]
	v_mov_b32_e32 v26, v34
	v_mov_b32_e32 v27, v34
	v_pk_mul_f32 v[24:25], v[24:25], v[26:27]
	v_pk_mul_f32 v[22:23], v[22:23], v[34:35]
	s_and_saveexec_b64 s[24:25], s[6:7]
	s_xor_b64 s[24:25], exec, s[24:25]
	s_cbranch_execz .LBB0_656
	v_and_b32_e32 v192, -8, v0
	s_mov_b64 s[50:51], vcc
	s_mov_b64 vcc, s[40:41]
	v_cndmask_b32_dpp v188, v23, v22, vcc quad_perm:[1,0,3,2] row_mask:0xf bank_mask:0xf
	v_cndmask_b32_dpp v190, v25, v24, vcc quad_perm:[1,0,3,2] row_mask:0xf bank_mask:0xf
	s_mov_b64 vcc, s[42:43]
	v_cndmask_b32_dpp v189, v22, v23, vcc quad_perm:[1,0,3,2] row_mask:0xf bank_mask:0xf
	v_cndmask_b32_dpp v191, v24, v25, vcc quad_perm:[1,0,3,2] row_mask:0xf bank_mask:0xf
	s_mov_b64 vcc, s[46:47]
	v_cndmask_b32_dpp v22, v190, v188, vcc quad_perm:[2,3,0,1] row_mask:0xf bank_mask:0xf
	v_cndmask_b32_dpp v23, v191, v189, vcc quad_perm:[2,3,0,1] row_mask:0xf bank_mask:0xf
	s_mov_b64 vcc, s[48:49]
	v_cndmask_b32_dpp v24, v188, v190, vcc quad_perm:[2,3,0,1] row_mask:0xf bank_mask:0xf
	v_cndmask_b32_dpp v25, v189, v191, vcc quad_perm:[2,3,0,1] row_mask:0xf bank_mask:0xf
	s_mov_b64 vcc, s[50:51]
	v_lshl_add_u32 v192, v162, 9, v192
	v_cvt_pk_bf16_f32 v25, v24, v25
	v_cvt_pk_bf16_f32 v24, v22, v23
	v_add_u32_e32 v192, v192, v226
	v_mov_b32_e32 v193, v1
	v_lshl_add_u64 v[192:193], v[66:67], 0, v[192:193]
	global_store_dwordx2 v[192:193], v[24:25], off

; __device__ __forceinline__ bf16_t f2bf(float x) { return (bf16_t)(cvt_pk_bf16(x, 0.f) & 0xffffu); }
; __device__ __forceinline__ void st_bf4(bf16_t* p, f32x4 v) { u32x2 w; w.x = cvt_pk_bf16(v[0], v[1]); w.y = cvt_pk_bf16(v[2], v[3]); *(u32x2*)p = w; }
;     __device__ __forceinline__ void operator()(const Acc& acc, const Unit& u, int wr, int wc, int fr, int fq) const {
;     ...
;             for (int m = 0; m < 4; ++m) { const int row = row0 + ai * 128 + m * 16; const float rs = rstd[row];
; #pragma unroll
;                 for (int bj = 0; bj < 2; ++bj)
; #pragma unroll
;                     for (int n = 0; n < 2; ++n) { const int col = col0 + bj * 128 + n * 16; const f32x4 v = acc[ai][bj][m][n] * rs;
;                         if (col < 512) st_bf4(Kb + (size_t)row * 512 + col, v);
;                         else {
; #pragma unroll
;                             for (int j = 0; j < 4; ++j) Vt[((size_t)(row >> 8) * 512 + (col - 512 + j)) * 256 + (row & 255)] = f2bf(v[j]); } } }
.LBB0_658:
	s_or_b64 exec, exec, s[24:25]
	v_mov_b32_e32 v22, v34
	v_mov_b32_e32 v23, v34
	v_pk_mul_f32 v[20:21], v[20:21], v[22:23]
	v_pk_mul_f32 v[18:19], v[18:19], v[34:35]
	s_and_saveexec_b64 s[24:25], s[8:9]
	s_xor_b64 s[24:25], exec, s[24:25]
	s_cbranch_execz .LBB0_660
	v_and_b32_e32 v192, -8, v0
	s_mov_b64 s[50:51], vcc
	s_mov_b64 vcc, s[40:41]
	v_cndmask_b32_dpp v188, v19, v18, vcc quad_perm:[1,0,3,2] row_mask:0xf bank_mask:0xf
	v_cndmask_b32_dpp v190, v21, v20, vcc quad_perm:[1,0,3,2] row_mask:0xf bank_mask:0xf
	s_mov_b64 vcc, s[42:43]
	v_cndmask_b32_dpp v189, v18, v19, vcc quad_perm:[1,0,3,2] row_mask:0xf bank_mask:0xf
	v_cndmask_b32_dpp v191, v20, v21, vcc quad_perm:[1,0,3,2] row_mask:0xf bank_mask:0xf
	s_mov_b64 vcc, s[46:47]
	v_cndmask_b32_dpp v18, v190, v188, vcc quad_perm:[2,3,0,1] row_mask:0xf bank_mask:0xf
	v_cndmask_b32_dpp v19, v191, v189, vcc quad_perm:[2,3,0,1] row_mask:0xf bank_mask:0xf
	s_mov_b64 vcc, s[48:49]
	v_cndmask_b32_dpp v20, v188, v190, vcc quad_perm:[2,3,0,1] row_mask:0xf bank_mask:0xf
	v_cndmask_b32_dpp v21, v189, v191, vcc quad_perm:[2,3,0,1] row_mask:0xf bank_mask:0xf
	s_mov_b64 vcc, s[50:51]
	v_lshl_add_u32 v192, v166, 9, v192
	v_cvt_pk_bf16_f32 v21, v20, v21
	v_cvt_pk_bf16_f32 v20, v18, v19
	v_add_u32_e32 v192, v192, v226
	v_mov_b32_e32 v193, v1
	v_lshl_add_u64 v[192:193], v[66:67], 0, v[192:193]
	global_store_dwordx2 v[192:193], v[20:21], off

;     __device__ __forceinline__ void operator()(const Acc& acc, const Unit& u, int wr, int wc, int fr, int fq) const {
;     ...
;             for (int m = 0; m < 4; ++m) { const int row = row0 + ai * 128 + m * 16; const float rs = rstd[row];
; #pragma unroll
;                 for (int bj = 0; bj < 2; ++bj)
; #pragma unroll
;                     for (int n = 0; n < 2; ++n) { const int col = col0 + bj * 128 + n * 16; const f32x4 v = acc[ai][bj][m][n] * rs;
.LBB0_662:
	s_or_b64 exec, exec, s[24:25]
	v_mov_b32_e32 v18, v200
	v_add_u32_e32 v20, 0xb0, v148
	v_lshlrev_b32_sdwa v0, v243, v20 dst_sel:DWORD dst_unused:UNUSED_PAD src0_sel:DWORD src1_sel:BYTE_0

; __device__ __forceinline__ bf16_t f2bf(float x) { return (bf16_t)(cvt_pk_bf16(x, 0.f) & 0xffffu); }
; __device__ __forceinline__ void st_bf4(bf16_t* p, f32x4 v) { u32x2 w; w.x = cvt_pk_bf16(v[0], v[1]); w.y = cvt_pk_bf16(v[2], v[3]); *(u32x2*)p = w; }
;     __device__ __forceinline__ void operator()(const Acc& acc, const Unit& u, int wr, int wc, int fr, int fq) const {
;     ...
;             for (int m = 0; m < 4; ++m) { const int row = row0 + ai * 128 + m * 16; const float rs = rstd[row];
; #pragma unroll
;                 for (int bj = 0; bj < 2; ++bj)
; #pragma unroll
;                     for (int n = 0; n < 2; ++n) { const int col = col0 + bj * 128 + n * 16; const f32x4 v = acc[ai][bj][m][n] * rs;
;                         if (col < 512) st_bf4(Kb + (size_t)row * 512 + col, v);
;                         else {
; #pragma unroll
;                             for (int j = 0; j < 4; ++j) Vt[((size_t)(row >> 8) * 512 + (col - 512 + j)) * 256 + (row & 255)] = f2bf(v[j]); } } }
	v_pk_mul_f32 v[16:17], v[16:17], v[18:19] op_sel_hi:[1,0]
	v_pk_mul_f32 v[22:23], v[14:15], v[18:19] op_sel_hi:[1,0]
	s_and_saveexec_b64 s[24:25], vcc
	s_xor_b64 s[24:25], exec, s[24:25]
	s_cbranch_execz .LBB0_664
	v_and_b32_e32 v192, -8, v0
	s_mov_b64 s[50:51], vcc
	s_mov_b64 vcc, s[40:41]
	v_cndmask_b32_dpp v188, v23, v22, vcc quad_perm:[1,0,3,2] row_mask:0xf bank_mask:0xf
	v_cndmask_b32_dpp v190, v17, v16, vcc quad_perm:[1,0,3,2] row_mask:0xf bank_mask:0xf
	s_mov_b64 vcc, s[42:43]
	v_cndmask_b32_dpp v189, v22, v23, vcc quad_perm:[1,0,3,2] row_mask:0xf bank_mask:0xf
	v_cndmask_b32_dpp v191, v16, v17, vcc quad_perm:[1,0,3,2] row_mask:0xf bank_mask:0xf
	s_mov_b64 vcc, s[46:47]
	v_cndmask_b32_dpp v22, v190, v188, vcc quad_perm:[2,3,0,1] row_mask:0xf bank_mask:0xf
	v_cndmask_b32_dpp v23, v191, v189, vcc quad_perm:[2,3,0,1] row_mask:0xf bank_mask:0xf
	s_mov_b64 vcc, s[48:49]
	v_cndmask_b32_dpp v16, v188, v190, vcc quad_perm:[2,3,0,1] row_mask:0xf bank_mask:0xf
	v_cndmask_b32_dpp v17, v189, v191, vcc quad_perm:[2,3,0,1] row_mask:0xf bank_mask:0xf
	s_mov_b64 vcc, s[50:51]
	v_lshl_add_u32 v192, v154, 9, v192
	v_cvt_pk_bf16_f32 v17, v16, v17
	v_cvt_pk_bf16_f32 v16, v22, v23
	v_add_u32_e32 v192, v192, v226
	v_mov_b32_e32 v193, v1
	v_lshl_add_u64 v[192:193], v[66:67], 0, v[192:193]
	global_store_dwordx2 v[192:193], v[16:17], off

; __device__ __forceinline__ bf16_t f2bf(float x) { return (bf16_t)(cvt_pk_bf16(x, 0.f) & 0xffffu); }
; __device__ __forceinline__ void st_bf4(bf16_t* p, f32x4 v) { u32x2 w; w.x = cvt_pk_bf16(v[0], v[1]); w.y = cvt_pk_bf16(v[2], v[3]); *(u32x2*)p = w; }
;     __device__ __forceinline__ void operator()(const Acc& acc, const Unit& u, int wr, int wc, int fr, int fq) const {
;     ...
;             for (int m = 0; m < 4; ++m) { const int row = row0 + ai * 128 + m * 16; const float rs = rstd[row];
; #pragma unroll
;                 for (int bj = 0; bj < 2; ++bj)
; #pragma unroll
;                     for (int n = 0; n < 2; ++n) { const int col = col0 + bj * 128 + n * 16; const f32x4 v = acc[ai][bj][m][n] * rs;
;                         if (col < 512) st_bf4(Kb + (size_t)row * 512 + col, v);
;                         else {
; #pragma unroll
;                             for (int j = 0; j < 4; ++j) Vt[((size_t)(row >> 8) * 512 + (col - 512 + j)) * 256 + (row & 255)] = f2bf(v[j]); } } }
.LBB0_666:
	s_or_b64 exec, exec, s[24:25]
	v_mov_b32_e32 v19, v18
	v_mov_b32_e32 v16, v18
	v_mov_b32_e32 v17, v18
	v_pk_mul_f32 v[12:13], v[12:13], v[16:17]
	v_pk_mul_f32 v[10:11], v[10:11], v[18:19]
	s_and_saveexec_b64 s[24:25], s[4:5]
	s_xor_b64 s[4:5], exec, s[24:25]
	s_cbranch_execz .LBB0_668
	v_and_b32_e32 v192, -8, v0
	s_mov_b64 s[50:51], vcc
	s_mov_b64 vcc, s[40:41]
	v_cndmask_b32_dpp v188, v11, v10, vcc quad_perm:[1,0,3,2] row_mask:0xf bank_mask:0xf
	v_cndmask_b32_dpp v190, v13, v12, vcc quad_perm:[1,0,3,2] row_mask:0xf bank_mask:0xf
	s_mov_b64 vcc, s[42:43]
	v_cndmask_b32_dpp v189, v10, v11, vcc quad_perm:[1,0,3,2] row_mask:0xf bank_mask:0xf
	v_cndmask_b32_dpp v191, v12, v13, vcc quad_perm:[1,0,3,2] row_mask:0xf bank_mask:0xf
	s_mov_b64 vcc, s[46:47]
	v_cndmask_b32_dpp v10, v190, v188, vcc quad_perm:[2,3,0,1] row_mask:0xf bank_mask:0xf
	v_cndmask_b32_dpp v11, v191, v189, vcc quad_perm:[2,3,0,1] row_mask:0xf bank_mask:0xf
	s_mov_b64 vcc, s[48:49]
	v_cndmask_b32_dpp v12, v188, v190, vcc quad_perm:[2,3,0,1] row_mask:0xf bank_mask:0xf
	v_cndmask_b32_dpp v13, v189, v191, vcc quad_perm:[2,3,0,1] row_mask:0xf bank_mask:0xf
	s_mov_b64 vcc, s[50:51]
	v_lshl_add_u32 v192, v158, 9, v192
	v_cvt_pk_bf16_f32 v13, v12, v13
	v_cvt_pk_bf16_f32 v12, v10, v11
	v_add_u32_e32 v192, v192, v226
	v_mov_b32_e32 v193, v1
	v_lshl_add_u64 v[192:193], v[66:67], 0, v[192:193]
	global_store_dwordx2 v[192:193], v[12:13], off

; __device__ __forceinline__ bf16_t f2bf(float x) { return (bf16_t)(cvt_pk_bf16(x, 0.f) & 0xffffu); }
; __device__ __forceinline__ void st_bf4(bf16_t* p, f32x4 v) { u32x2 w; w.x = cvt_pk_bf16(v[0], v[1]); w.y = cvt_pk_bf16(v[2], v[3]); *(u32x2*)p = w; }
;     __device__ __forceinline__ void operator()(const Acc& acc, const Unit& u, int wr, int wc, int fr, int fq) const {
;     ...
;             for (int m = 0; m < 4; ++m) { const int row = row0 + ai * 128 + m * 16; const float rs = rstd[row];
; #pragma unroll
;                 for (int bj = 0; bj < 2; ++bj)
; #pragma unroll
;                     for (int n = 0; n < 2; ++n) { const int col = col0 + bj * 128 + n * 16; const f32x4 v = acc[ai][bj][m][n] * rs;
;                         if (col < 512) st_bf4(Kb + (size_t)row * 512 + col, v);
;                         else {
; #pragma unroll
;                             for (int j = 0; j < 4; ++j) Vt[((size_t)(row >> 8) * 512 + (col - 512 + j)) * 256 + (row & 255)] = f2bf(v[j]); } } }
.LBB0_670:
	s_or_b64 exec, exec, s[4:5]
	v_mov_b32_e32 v10, v18
	v_mov_b32_e32 v11, v18
	v_pk_mul_f32 v[8:9], v[8:9], v[10:11]
	v_pk_mul_f32 v[6:7], v[6:7], v[18:19]
	s_and_saveexec_b64 s[4:5], s[6:7]
	s_xor_b64 s[4:5], exec, s[4:5]
	s_cbranch_execz .LBB0_672
	v_and_b32_e32 v192, -8, v0
	s_mov_b64 s[50:51], vcc
	s_mov_b64 vcc, s[40:41]
	v_cndmask_b32_dpp v188, v7, v6, vcc quad_perm:[1,0,3,2] row_mask:0xf bank_mask:0xf
	v_cndmask_b32_dpp v190, v9, v8, vcc quad_perm:[1,0,3,2] row_mask:0xf bank_mask:0xf
	s_mov_b64 vcc, s[42:43]
	v_cndmask_b32_dpp v189, v6, v7, vcc quad_perm:[1,0,3,2] row_mask:0xf bank_mask:0xf
	v_cndmask_b32_dpp v191, v8, v9, vcc quad_perm:[1,0,3,2] row_mask:0xf bank_mask:0xf
	s_mov_b64 vcc, s[46:47]
	v_cndmask_b32_dpp v6, v190, v188, vcc quad_perm:[2,3,0,1] row_mask:0xf bank_mask:0xf
	v_cndmask_b32_dpp v7, v191, v189, vcc quad_perm:[2,3,0,1] row_mask:0xf bank_mask:0xf
	s_mov_b64 vcc, s[48:49]
	v_cndmask_b32_dpp v8, v188, v190, vcc quad_perm:[2,3,0,1] row_mask:0xf bank_mask:0xf
	v_cndmask_b32_dpp v9, v189, v191, vcc quad_perm:[2,3,0,1] row_mask:0xf bank_mask:0xf
	s_mov_b64 vcc, s[50:51]
	v_lshl_add_u32 v192, v162, 9, v192
	v_cvt_pk_bf16_f32 v9, v8, v9
	v_cvt_pk_bf16_f32 v8, v6, v7
	v_add_u32_e32 v192, v192, v226
	v_mov_b32_e32 v193, v1
	v_lshl_add_u64 v[192:193], v[66:67], 0, v[192:193]
	global_store_dwordx2 v[192:193], v[8:9], off

; __device__ __forceinline__ bf16_t f2bf(float x) { return (bf16_t)(cvt_pk_bf16(x, 0.f) & 0xffffu); }
; __device__ __forceinline__ void st_bf4(bf16_t* p, f32x4 v) { u32x2 w; w.x = cvt_pk_bf16(v[0], v[1]); w.y = cvt_pk_bf16(v[2], v[3]); *(u32x2*)p = w; }
;     __device__ __forceinline__ void operator()(const Acc& acc, const Unit& u, int wr, int wc, int fr, int fq) const {
;     ...
;             for (int m = 0; m < 4; ++m) { const int row = row0 + ai * 128 + m * 16; const float rs = rstd[row];
; #pragma unroll
;                 for (int bj = 0; bj < 2; ++bj)
; #pragma unroll
;                     for (int n = 0; n < 2; ++n) { const int col = col0 + bj * 128 + n * 16; const f32x4 v = acc[ai][bj][m][n] * rs;
;                         if (col < 512) st_bf4(Kb + (size_t)row * 512 + col, v);
;                         else {
; #pragma unroll
;                             for (int j = 0; j < 4; ++j) Vt[((size_t)(row >> 8) * 512 + (col - 512 + j)) * 256 + (row & 255)] = f2bf(v[j]); } } }
.LBB0_674:
	s_or_b64 exec, exec, s[4:5]
	v_mov_b32_e32 v6, v18
	v_mov_b32_e32 v7, v18
	v_pk_mul_f32 v[4:5], v[4:5], v[6:7]
	v_pk_mul_f32 v[2:3], v[2:3], v[18:19]
	s_and_saveexec_b64 s[4:5], s[8:9]
	s_xor_b64 s[4:5], exec, s[4:5]
	s_cbranch_execz .LBB0_676
	v_and_b32_e32 v192, -8, v0
	s_mov_b64 s[50:51], vcc
	s_mov_b64 vcc, s[40:41]
	v_cndmask_b32_dpp v188, v3, v2, vcc quad_perm:[1,0,3,2] row_mask:0xf bank_mask:0xf
	v_cndmask_b32_dpp v190, v5, v4, vcc quad_perm:[1,0,3,2] row_mask:0xf bank_mask:0xf
	s_mov_b64 vcc, s[42:43]
	v_cndmask_b32_dpp v189, v2, v3, vcc quad_perm:[1,0,3,2] row_mask:0xf bank_mask:0xf
	v_cndmask_b32_dpp v191, v4, v5, vcc quad_perm:[1,0,3,2] row_mask:0xf bank_mask:0xf
	s_mov_b64 vcc, s[46:47]
	v_cndmask_b32_dpp v2, v190, v188, vcc quad_perm:[2,3,0,1] row_mask:0xf bank_mask:0xf
	v_cndmask_b32_dpp v3, v191, v189, vcc quad_perm:[2,3,0,1] row_mask:0xf bank_mask:0xf
	s_mov_b64 vcc, s[48:49]
	v_cndmask_b32_dpp v4, v188, v190, vcc quad_perm:[2,3,0,1] row_mask:0xf bank_mask:0xf
	v_cndmask_b32_dpp v5, v189, v191, vcc quad_perm:[2,3,0,1] row_mask:0xf bank_mask:0xf
	s_mov_b64 vcc, s[50:51]
	v_lshl_add_u32 v192, v166, 9, v192
	v_cvt_pk_bf16_f32 v5, v4, v5
	v_cvt_pk_bf16_f32 v4, v2, v3
	v_add_u32_e32 v192, v192, v226
	v_mov_b32_e32 v193, v1
	v_lshl_add_u64 v[192:193], v[66:67], 0, v[192:193]
	global_store_dwordx2 v[192:193], v[4:5], off
